# PEER down2: xor-4/2/1 partial-dot redistribution via DPP adds (row_shl/shr:4 with bank masks, quad_perm) instead of cndmask+ds_bpermute; removes 14 LDS round trips + 8 VALU per token
# speedup vs baseline: 1.0193x; 1.0112x over previous
; DI float bflo(u32 u) { return __uint_as_float(u << 16); }
; DI float bfhi(u32 u) { return __uint_as_float(u & 0xffff0000u); }
; DI void dn2_math(const u32x4 (&W)[16], u32x4 x0, u32x4 x1, float* __restrict__ parow, int lane) {
;   f2 xf[8];
; #pragma unroll
;   for (int q = 0; q < 4; ++q) { xf[q] = f2{bflo(x0[q]), bfhi(x0[q])}; xf[4 + q] = f2{bflo(x1[q]), bfhi(x1[q])}; }
;   float pv[16];
; #pragma unroll
;   for (int j = 0; j < 16; ++j) {
;     f2 s2 = {0.f, 0.f};
; #pragma unroll
;     for (int d = 0; d < 4; ++d) {
;       f2 lo = __builtin_amdgcn_cvt_pk_f32_fp8((int)W[j][d], false);
;       f2 hi = __builtin_amdgcn_cvt_pk_f32_fp8((int)W[j][d], true);
;       s2 = lo * xf[2 * d] + s2;
;       s2 = hi * xf[2 * d + 1] + s2;
;     }
;     pv[j] = s2.x + s2.y;
;   }
.LBB0_693:
	s_add_i32 s46, s46, 2
	s_waitcnt vmcnt(19)
	v_cvt_pk_f32_fp8_e32 v[210:211], v134
	v_cvt_pk_f32_fp8_sdwa v[212:213], v134 src0_sel:WORD_1
	v_cvt_pk_f32_fp8_e32 v[214:215], v135
	s_waitcnt vmcnt(2)
	v_lshlrev_b32_e32 v204, 16, v142
	v_and_b32_e32 v205, 0xffff0000, v142
	v_cvt_pk_f32_fp8_sdwa v[134:135], v135 src0_sel:WORD_1
	v_lshlrev_b32_e32 v206, 16, v143
	v_and_b32_e32 v207, 0xffff0000, v143
	v_pk_fma_f32 v[210:211], v[210:211], v[204:205], 0 op_sel_hi:[1,1,0]
	v_lshlrev_b32_e32 v208, 16, v144
	v_and_b32_e32 v209, 0xffff0000, v144
	v_pk_fma_f32 v[210:211], v[212:213], v[206:207], v[210:211]
	v_lshlrev_b32_e32 v144, 16, v145
	v_and_b32_e32 v145, 0xffff0000, v145
	v_pk_fma_f32 v[210:211], v[214:215], v[208:209], v[210:211]
	v_cvt_pk_f32_fp8_sdwa v[212:213], v136 src0_sel:WORD_1
	v_pk_fma_f32 v[134:135], v[134:135], v[144:145], v[210:211]
	v_cvt_pk_f32_fp8_e32 v[210:211], v136
	v_cvt_pk_f32_fp8_e32 v[214:215], v137
	v_lshlrev_b32_e32 v202, 16, v138
	v_and_b32_e32 v203, 0xffff0000, v138
	v_cvt_pk_f32_fp8_sdwa v[136:137], v137 src0_sel:WORD_1
	v_lshlrev_b32_e32 v138, 16, v139
	v_and_b32_e32 v139, 0xffff0000, v139
	v_pk_fma_f32 v[134:135], v[210:211], v[202:203], v[134:135]
	v_lshlrev_b32_e32 v142, 16, v140
	v_and_b32_e32 v143, 0xffff0000, v140
	v_pk_fma_f32 v[134:135], v[212:213], v[138:139], v[134:135]
	v_lshlrev_b32_e32 v140, 16, v141
	v_and_b32_e32 v141, 0xffff0000, v141
	v_pk_fma_f32 v[134:135], v[214:215], v[142:143], v[134:135]
	v_cvt_pk_f32_fp8_e32 v[210:211], v131
	v_pk_fma_f32 v[134:135], v[136:137], v[140:141], v[134:135]
	v_cvt_pk_f32_fp8_sdwa v[136:137], v130 src0_sel:WORD_1
	v_add_f32_e32 v167, v134, v135
	v_cvt_pk_f32_fp8_e32 v[134:135], v130
	v_cvt_pk_f32_fp8_sdwa v[130:131], v131 src0_sel:WORD_1
	v_pk_fma_f32 v[134:135], v[134:135], v[204:205], 0 op_sel_hi:[1,1,0]
	s_nop 0
	v_pk_fma_f32 v[134:135], v[136:137], v[206:207], v[134:135]
	v_cvt_pk_f32_fp8_sdwa v[136:137], v132 src0_sel:WORD_1
	v_pk_fma_f32 v[134:135], v[210:211], v[208:209], v[134:135]
	v_cvt_pk_f32_fp8_e32 v[210:211], v133
	v_pk_fma_f32 v[130:131], v[130:131], v[144:145], v[134:135]
	v_cvt_pk_f32_fp8_e32 v[134:135], v132
	v_cvt_pk_f32_fp8_sdwa v[132:133], v133 src0_sel:WORD_1
	v_pk_fma_f32 v[130:131], v[134:135], v[202:203], v[130:131]
	s_nop 0
	v_pk_fma_f32 v[130:131], v[136:137], v[138:139], v[130:131]
	v_cvt_pk_f32_fp8_e32 v[134:135], v127
	v_pk_fma_f32 v[130:131], v[210:211], v[142:143], v[130:131]
	s_nop 0
	v_pk_fma_f32 v[130:131], v[132:133], v[140:141], v[130:131]
	v_cvt_pk_f32_fp8_sdwa v[132:133], v126 src0_sel:WORD_1
	v_add_f32_e32 v136, v130, v131
	v_cvt_pk_f32_fp8_e32 v[130:131], v126
	v_cvt_pk_f32_fp8_sdwa v[126:127], v127 src0_sel:WORD_1
	v_pk_fma_f32 v[130:131], v[130:131], v[204:205], 0 op_sel_hi:[1,1,0]
	s_nop 0
	v_pk_fma_f32 v[130:131], v[132:133], v[206:207], v[130:131]
	v_cvt_pk_f32_fp8_sdwa v[132:133], v128 src0_sel:WORD_1
	v_pk_fma_f32 v[130:131], v[134:135], v[208:209], v[130:131]
	v_cvt_pk_f32_fp8_e32 v[134:135], v129
	v_pk_fma_f32 v[126:127], v[126:127], v[144:145], v[130:131]
	v_cvt_pk_f32_fp8_e32 v[130:131], v128
	v_cvt_pk_f32_fp8_sdwa v[128:129], v129 src0_sel:WORD_1
	v_pk_fma_f32 v[126:127], v[130:131], v[202:203], v[126:127]
	s_nop 0
	v_pk_fma_f32 v[126:127], v[132:133], v[138:139], v[126:127]
	v_cvt_pk_f32_fp8_e32 v[130:131], v123
	v_pk_fma_f32 v[126:127], v[134:135], v[142:143], v[126:127]
	s_nop 0
	v_pk_fma_f32 v[126:127], v[128:129], v[140:141], v[126:127]
	v_cvt_pk_f32_fp8_sdwa v[128:129], v122 src0_sel:WORD_1
	v_add_f32_e32 v132, v126, v127
	v_cvt_pk_f32_fp8_e32 v[126:127], v122
	v_cvt_pk_f32_fp8_sdwa v[122:123], v123 src0_sel:WORD_1
	v_pk_fma_f32 v[126:127], v[126:127], v[204:205], 0 op_sel_hi:[1,1,0]
	s_nop 0
	v_pk_fma_f32 v[126:127], v[128:129], v[206:207], v[126:127]
	v_cvt_pk_f32_fp8_sdwa v[128:129], v124 src0_sel:WORD_1
	v_pk_fma_f32 v[126:127], v[130:131], v[208:209], v[126:127]
	v_cvt_pk_f32_fp8_e32 v[130:131], v125
	v_pk_fma_f32 v[122:123], v[122:123], v[144:145], v[126:127]
	v_cvt_pk_f32_fp8_e32 v[126:127], v124
	v_cvt_pk_f32_fp8_sdwa v[124:125], v125 src0_sel:WORD_1
	v_pk_fma_f32 v[122:123], v[126:127], v[202:203], v[122:123]
	s_nop 0
	v_pk_fma_f32 v[122:123], v[128:129], v[138:139], v[122:123]
	v_cvt_pk_f32_fp8_e32 v[126:127], v119
	v_pk_fma_f32 v[122:123], v[130:131], v[142:143], v[122:123]
	s_nop 0
	v_pk_fma_f32 v[122:123], v[124:125], v[140:141], v[122:123]
	v_cvt_pk_f32_fp8_sdwa v[124:125], v118 src0_sel:WORD_1
	v_add_f32_e32 v128, v122, v123
	v_cvt_pk_f32_fp8_e32 v[122:123], v118
	v_cvt_pk_f32_fp8_sdwa v[118:119], v119 src0_sel:WORD_1
	v_pk_fma_f32 v[122:123], v[122:123], v[204:205], 0 op_sel_hi:[1,1,0]
	s_nop 0
	v_pk_fma_f32 v[122:123], v[124:125], v[206:207], v[122:123]
	v_cvt_pk_f32_fp8_sdwa v[124:125], v120 src0_sel:WORD_1
	v_pk_fma_f32 v[122:123], v[126:127], v[208:209], v[122:123]
	v_cvt_pk_f32_fp8_e32 v[126:127], v121
	v_pk_fma_f32 v[118:119], v[118:119], v[144:145], v[122:123]
	v_cvt_pk_f32_fp8_e32 v[122:123], v120
	v_cvt_pk_f32_fp8_sdwa v[120:121], v121 src0_sel:WORD_1
	v_pk_fma_f32 v[118:119], v[122:123], v[202:203], v[118:119]
	s_nop 0
	v_pk_fma_f32 v[118:119], v[124:125], v[138:139], v[118:119]
	v_cvt_pk_f32_fp8_e32 v[122:123], v115
	v_pk_fma_f32 v[118:119], v[126:127], v[142:143], v[118:119]
	s_nop 0
	v_pk_fma_f32 v[118:119], v[120:121], v[140:141], v[118:119]
	v_cvt_pk_f32_fp8_sdwa v[120:121], v114 src0_sel:WORD_1
	v_add_f32_e32 v124, v118, v119
	v_cvt_pk_f32_fp8_e32 v[118:119], v114
	v_cvt_pk_f32_fp8_sdwa v[114:115], v115 src0_sel:WORD_1
	v_pk_fma_f32 v[118:119], v[118:119], v[204:205], 0 op_sel_hi:[1,1,0]
	s_nop 0
	v_pk_fma_f32 v[118:119], v[120:121], v[206:207], v[118:119]
; DI void dn2_math(const u32x4 (&W)[16], u32x4 x0, u32x4 x1, float* __restrict__ parow, int lane) {
;     ...
;   for (int j = 0; j < 16; ++j) {
;     f2 s2 = {0.f, 0.f};
; #pragma unroll
;     for (int d = 0; d < 4; ++d) {
;       f2 lo = __builtin_amdgcn_cvt_pk_f32_fp8((int)W[j][d], false);
;       f2 hi = __builtin_amdgcn_cvt_pk_f32_fp8((int)W[j][d], true);
;       s2 = lo * xf[2 * d] + s2;
;       s2 = hi * xf[2 * d + 1] + s2;
;     }
;     pv[j] = s2.x + s2.y;
;   }
	v_cvt_pk_f32_fp8_sdwa v[120:121], v116 src0_sel:WORD_1
	v_pk_fma_f32 v[118:119], v[122:123], v[208:209], v[118:119]
	v_cvt_pk_f32_fp8_e32 v[122:123], v117
	v_pk_fma_f32 v[114:115], v[114:115], v[144:145], v[118:119]
	v_cvt_pk_f32_fp8_e32 v[118:119], v116
	v_cvt_pk_f32_fp8_sdwa v[116:117], v117 src0_sel:WORD_1
	v_pk_fma_f32 v[114:115], v[118:119], v[202:203], v[114:115]
	s_nop 0
	v_pk_fma_f32 v[114:115], v[120:121], v[138:139], v[114:115]
	v_cvt_pk_f32_fp8_e32 v[118:119], v111
	v_pk_fma_f32 v[114:115], v[122:123], v[142:143], v[114:115]
	s_nop 0
	v_pk_fma_f32 v[114:115], v[116:117], v[140:141], v[114:115]
	v_cvt_pk_f32_fp8_sdwa v[116:117], v110 src0_sel:WORD_1
	v_add_f32_e32 v120, v114, v115
	v_cvt_pk_f32_fp8_e32 v[114:115], v110
	v_cvt_pk_f32_fp8_sdwa v[110:111], v111 src0_sel:WORD_1
	v_pk_fma_f32 v[114:115], v[114:115], v[204:205], 0 op_sel_hi:[1,1,0]
	s_nop 0
	v_pk_fma_f32 v[114:115], v[116:117], v[206:207], v[114:115]
	v_cvt_pk_f32_fp8_sdwa v[116:117], v112 src0_sel:WORD_1
	v_pk_fma_f32 v[114:115], v[118:119], v[208:209], v[114:115]
	v_cvt_pk_f32_fp8_e32 v[118:119], v113
	v_pk_fma_f32 v[110:111], v[110:111], v[144:145], v[114:115]
	v_cvt_pk_f32_fp8_e32 v[114:115], v112
	v_cvt_pk_f32_fp8_sdwa v[112:113], v113 src0_sel:WORD_1
	v_pk_fma_f32 v[110:111], v[114:115], v[202:203], v[110:111]
	s_nop 0
	v_pk_fma_f32 v[110:111], v[116:117], v[138:139], v[110:111]
	v_cvt_pk_f32_fp8_e32 v[114:115], v107
	v_pk_fma_f32 v[110:111], v[118:119], v[142:143], v[110:111]
	s_nop 0
	v_pk_fma_f32 v[110:111], v[112:113], v[140:141], v[110:111]
	v_cvt_pk_f32_fp8_sdwa v[112:113], v106 src0_sel:WORD_1
	v_add_f32_e32 v116, v110, v111
	v_cvt_pk_f32_fp8_e32 v[110:111], v106
	v_cvt_pk_f32_fp8_sdwa v[106:107], v107 src0_sel:WORD_1
	v_pk_fma_f32 v[110:111], v[110:111], v[204:205], 0 op_sel_hi:[1,1,0]
	s_nop 0
	v_pk_fma_f32 v[110:111], v[112:113], v[206:207], v[110:111]
	v_cvt_pk_f32_fp8_sdwa v[112:113], v108 src0_sel:WORD_1
	v_pk_fma_f32 v[110:111], v[114:115], v[208:209], v[110:111]
	v_cvt_pk_f32_fp8_e32 v[114:115], v109
	v_pk_fma_f32 v[106:107], v[106:107], v[144:145], v[110:111]
	v_cvt_pk_f32_fp8_e32 v[110:111], v108
	v_cvt_pk_f32_fp8_sdwa v[108:109], v109 src0_sel:WORD_1
	v_pk_fma_f32 v[106:107], v[110:111], v[202:203], v[106:107]
	s_nop 0
	v_pk_fma_f32 v[106:107], v[112:113], v[138:139], v[106:107]
	v_cvt_pk_f32_fp8_e32 v[110:111], v103
	v_pk_fma_f32 v[106:107], v[114:115], v[142:143], v[106:107]
	s_nop 0
	v_pk_fma_f32 v[106:107], v[108:109], v[140:141], v[106:107]
	v_cvt_pk_f32_fp8_sdwa v[108:109], v102 src0_sel:WORD_1
	v_add_f32_e32 v112, v106, v107
	v_cvt_pk_f32_fp8_e32 v[106:107], v102
	v_cvt_pk_f32_fp8_sdwa v[102:103], v103 src0_sel:WORD_1
	v_pk_fma_f32 v[106:107], v[106:107], v[204:205], 0 op_sel_hi:[1,1,0]
	s_nop 0
	v_pk_fma_f32 v[106:107], v[108:109], v[206:207], v[106:107]
	v_cvt_pk_f32_fp8_sdwa v[108:109], v104 src0_sel:WORD_1
	v_pk_fma_f32 v[106:107], v[110:111], v[208:209], v[106:107]
	v_cvt_pk_f32_fp8_e32 v[110:111], v105
	v_pk_fma_f32 v[102:103], v[102:103], v[144:145], v[106:107]
	v_cvt_pk_f32_fp8_e32 v[106:107], v104
	v_cvt_pk_f32_fp8_sdwa v[104:105], v105 src0_sel:WORD_1
	v_pk_fma_f32 v[102:103], v[106:107], v[202:203], v[102:103]
	s_nop 0
	v_pk_fma_f32 v[102:103], v[108:109], v[138:139], v[102:103]
	v_cvt_pk_f32_fp8_e32 v[106:107], v99
	v_pk_fma_f32 v[102:103], v[110:111], v[142:143], v[102:103]
	s_nop 0
	v_pk_fma_f32 v[102:103], v[104:105], v[140:141], v[102:103]
	v_cvt_pk_f32_fp8_sdwa v[104:105], v98 src0_sel:WORD_1
	v_add_f32_e32 v108, v102, v103
	v_cvt_pk_f32_fp8_e32 v[102:103], v98
	v_cvt_pk_f32_fp8_sdwa v[98:99], v99 src0_sel:WORD_1
	v_pk_fma_f32 v[102:103], v[102:103], v[204:205], 0 op_sel_hi:[1,1,0]
	s_nop 0
	v_pk_fma_f32 v[102:103], v[104:105], v[206:207], v[102:103]
	v_cvt_pk_f32_fp8_sdwa v[104:105], v100 src0_sel:WORD_1
	v_pk_fma_f32 v[102:103], v[106:107], v[208:209], v[102:103]
	v_cvt_pk_f32_fp8_e32 v[106:107], v101
	v_pk_fma_f32 v[98:99], v[98:99], v[144:145], v[102:103]
	v_cvt_pk_f32_fp8_e32 v[102:103], v100
	v_cvt_pk_f32_fp8_sdwa v[100:101], v101 src0_sel:WORD_1
	v_pk_fma_f32 v[98:99], v[102:103], v[202:203], v[98:99]
	s_nop 0
	v_pk_fma_f32 v[98:99], v[104:105], v[138:139], v[98:99]
	v_cvt_pk_f32_fp8_e32 v[102:103], v95
	v_pk_fma_f32 v[98:99], v[106:107], v[142:143], v[98:99]
	s_nop 0
	v_pk_fma_f32 v[98:99], v[100:101], v[140:141], v[98:99]
	v_cvt_pk_f32_fp8_sdwa v[100:101], v94 src0_sel:WORD_1
	v_add_f32_e32 v104, v98, v99
	v_cvt_pk_f32_fp8_e32 v[98:99], v94
	v_cvt_pk_f32_fp8_sdwa v[94:95], v95 src0_sel:WORD_1
	v_pk_fma_f32 v[98:99], v[98:99], v[204:205], 0 op_sel_hi:[1,1,0]
	s_nop 0
	v_pk_fma_f32 v[98:99], v[100:101], v[206:207], v[98:99]
	v_cvt_pk_f32_fp8_sdwa v[100:101], v96 src0_sel:WORD_1
	v_pk_fma_f32 v[98:99], v[102:103], v[208:209], v[98:99]
	v_cvt_pk_f32_fp8_e32 v[102:103], v97
	v_pk_fma_f32 v[94:95], v[94:95], v[144:145], v[98:99]
	v_cvt_pk_f32_fp8_e32 v[98:99], v96
	v_cvt_pk_f32_fp8_sdwa v[96:97], v97 src0_sel:WORD_1
	v_pk_fma_f32 v[94:95], v[98:99], v[202:203], v[94:95]
	s_nop 0
	v_pk_fma_f32 v[94:95], v[100:101], v[138:139], v[94:95]
	v_cvt_pk_f32_fp8_e32 v[98:99], v91
	v_pk_fma_f32 v[94:95], v[102:103], v[142:143], v[94:95]
	s_nop 0
	v_pk_fma_f32 v[94:95], v[96:97], v[140:141], v[94:95]
	v_cvt_pk_f32_fp8_sdwa v[96:97], v90 src0_sel:WORD_1
	v_add_f32_e32 v100, v94, v95
	v_cvt_pk_f32_fp8_e32 v[94:95], v90
	v_cvt_pk_f32_fp8_sdwa v[90:91], v91 src0_sel:WORD_1
	v_pk_fma_f32 v[94:95], v[94:95], v[204:205], 0 op_sel_hi:[1,1,0]
	s_nop 0
	v_pk_fma_f32 v[94:95], v[96:97], v[206:207], v[94:95]
	v_cvt_pk_f32_fp8_sdwa v[96:97], v92 src0_sel:WORD_1
	v_pk_fma_f32 v[94:95], v[98:99], v[208:209], v[94:95]
	v_cvt_pk_f32_fp8_e32 v[98:99], v93
; DI void dn2_math(const u32x4 (&W)[16], u32x4 x0, u32x4 x1, float* __restrict__ parow, int lane) {
;     ...
;   for (int j = 0; j < 16; ++j) {
;     f2 s2 = {0.f, 0.f};
; #pragma unroll
;     for (int d = 0; d < 4; ++d) {
;       f2 lo = __builtin_amdgcn_cvt_pk_f32_fp8((int)W[j][d], false);
;       f2 hi = __builtin_amdgcn_cvt_pk_f32_fp8((int)W[j][d], true);
;       s2 = lo * xf[2 * d] + s2;
;       s2 = hi * xf[2 * d + 1] + s2;
;     }
;     pv[j] = s2.x + s2.y;
;   }
;   const bool b2 = lane & 4, b1 = lane & 2, b0 = lane & 1;
;   float q8[8];
; #pragma unroll
;   for (int i = 0; i < 8; ++i) { float snd = b2 ? pv[i] : pv[i + 8]; float kp = b2 ? pv[i + 8] : pv[i]; q8[i] = kp + __shfl_xor(snd, 4); }
;   float q4[4];
; #pragma unroll
;   for (int i = 0; i < 4; ++i) { float snd = b1 ? q8[i] : q8[i + 4]; float kp = b1 ? q8[i + 4] : q8[i]; q4[i] = kp + __shfl_xor(snd, 2); }
;   float r2[2];
; #pragma unroll
;   for (int i = 0; i < 2; ++i) { float snd = b0 ? q4[i] : q4[i + 2]; float kp = b0 ? q4[i + 2] : q4[i]; r2[i] = kp + __shfl_xor(snd, 1); }
;   const int j0 = (b0 ? 2 : 0) + (b1 ? 4 : 0) + (b2 ? 8 : 0);
;   const int grp = lane >> 3;
;   parow[8 * j0 + grp] = r2[0];
;   parow[8 * (j0 + 1) + grp] = r2[1];
	v_pk_fma_f32 v[90:91], v[90:91], v[144:145], v[94:95]
	v_cvt_pk_f32_fp8_e32 v[94:95], v92
	v_cvt_pk_f32_fp8_sdwa v[92:93], v93 src0_sel:WORD_1
	v_pk_fma_f32 v[90:91], v[94:95], v[202:203], v[90:91]
	s_nop 0
	v_pk_fma_f32 v[90:91], v[96:97], v[138:139], v[90:91]
	v_cvt_pk_f32_fp8_e32 v[94:95], v87
	v_pk_fma_f32 v[90:91], v[98:99], v[142:143], v[90:91]
	s_nop 0
	v_pk_fma_f32 v[90:91], v[92:93], v[140:141], v[90:91]
	v_cvt_pk_f32_fp8_sdwa v[92:93], v86 src0_sel:WORD_1
	v_add_f32_e32 v96, v90, v91
	v_cvt_pk_f32_fp8_e32 v[90:91], v86
	v_cvt_pk_f32_fp8_sdwa v[86:87], v87 src0_sel:WORD_1
	v_pk_fma_f32 v[90:91], v[90:91], v[204:205], 0 op_sel_hi:[1,1,0]
	s_nop 0
	v_pk_fma_f32 v[90:91], v[92:93], v[206:207], v[90:91]
	v_cvt_pk_f32_fp8_sdwa v[92:93], v88 src0_sel:WORD_1
	v_pk_fma_f32 v[90:91], v[94:95], v[208:209], v[90:91]
	v_cvt_pk_f32_fp8_e32 v[94:95], v89
	v_pk_fma_f32 v[86:87], v[86:87], v[144:145], v[90:91]
	v_cvt_pk_f32_fp8_e32 v[90:91], v88
	v_cvt_pk_f32_fp8_sdwa v[88:89], v89 src0_sel:WORD_1
	v_pk_fma_f32 v[86:87], v[90:91], v[202:203], v[86:87]
	s_nop 0
	v_pk_fma_f32 v[86:87], v[92:93], v[138:139], v[86:87]
	v_cvt_pk_f32_fp8_e32 v[90:91], v83
	v_pk_fma_f32 v[86:87], v[94:95], v[142:143], v[86:87]
	s_nop 0
	v_pk_fma_f32 v[86:87], v[88:89], v[140:141], v[86:87]
	v_cvt_pk_f32_fp8_sdwa v[88:89], v82 src0_sel:WORD_1
	v_add_f32_e32 v92, v86, v87
	v_cvt_pk_f32_fp8_e32 v[86:87], v82
	v_cvt_pk_f32_fp8_sdwa v[82:83], v83 src0_sel:WORD_1
	v_pk_fma_f32 v[86:87], v[86:87], v[204:205], 0 op_sel_hi:[1,1,0]
	s_nop 0
	v_pk_fma_f32 v[86:87], v[88:89], v[206:207], v[86:87]
	v_cvt_pk_f32_fp8_sdwa v[88:89], v84 src0_sel:WORD_1
	v_pk_fma_f32 v[86:87], v[90:91], v[208:209], v[86:87]
	v_cvt_pk_f32_fp8_e32 v[90:91], v85
	v_pk_fma_f32 v[82:83], v[82:83], v[144:145], v[86:87]
	v_cvt_pk_f32_fp8_e32 v[86:87], v84
	v_cvt_pk_f32_fp8_sdwa v[84:85], v85 src0_sel:WORD_1
	v_pk_fma_f32 v[82:83], v[86:87], v[202:203], v[82:83]
	s_nop 0
	v_pk_fma_f32 v[82:83], v[88:89], v[138:139], v[82:83]
	v_cvt_pk_f32_fp8_e32 v[86:87], v79
	v_pk_fma_f32 v[82:83], v[90:91], v[142:143], v[82:83]
	s_nop 0
	v_pk_fma_f32 v[82:83], v[84:85], v[140:141], v[82:83]
	v_cvt_pk_f32_fp8_sdwa v[84:85], v78 src0_sel:WORD_1
	v_add_f32_e32 v88, v82, v83
	v_cvt_pk_f32_fp8_e32 v[82:83], v78
	v_cvt_pk_f32_fp8_sdwa v[78:79], v79 src0_sel:WORD_1
	v_pk_fma_f32 v[82:83], v[82:83], v[204:205], 0 op_sel_hi:[1,1,0]
	s_nop 0
	v_pk_fma_f32 v[82:83], v[84:85], v[206:207], v[82:83]
	v_cvt_pk_f32_fp8_sdwa v[84:85], v80 src0_sel:WORD_1
	v_pk_fma_f32 v[82:83], v[86:87], v[208:209], v[82:83]
	v_cvt_pk_f32_fp8_e32 v[86:87], v81
	v_pk_fma_f32 v[78:79], v[78:79], v[144:145], v[82:83]
	v_cvt_pk_f32_fp8_e32 v[82:83], v80
	v_cvt_pk_f32_fp8_sdwa v[80:81], v81 src0_sel:WORD_1
	v_pk_fma_f32 v[78:79], v[82:83], v[202:203], v[78:79]
	s_nop 0
	v_pk_fma_f32 v[78:79], v[84:85], v[138:139], v[78:79]
	v_cvt_pk_f32_fp8_e32 v[82:83], v75
	v_pk_fma_f32 v[78:79], v[86:87], v[142:143], v[78:79]
	s_nop 0
	v_pk_fma_f32 v[78:79], v[80:81], v[140:141], v[78:79]
	v_cvt_pk_f32_fp8_sdwa v[80:81], v74 src0_sel:WORD_1
	v_add_f32_e32 v84, v78, v79
	v_cvt_pk_f32_fp8_e32 v[78:79], v74
	v_cvt_pk_f32_fp8_sdwa v[74:75], v75 src0_sel:WORD_1
	v_pk_fma_f32 v[78:79], v[78:79], v[204:205], 0 op_sel_hi:[1,1,0]
	s_nop 0
	v_pk_fma_f32 v[78:79], v[80:81], v[206:207], v[78:79]
	v_cvt_pk_f32_fp8_sdwa v[80:81], v76 src0_sel:WORD_1
	v_pk_fma_f32 v[78:79], v[82:83], v[208:209], v[78:79]
	v_cvt_pk_f32_fp8_e32 v[82:83], v77
	v_pk_fma_f32 v[74:75], v[74:75], v[144:145], v[78:79]
	v_cvt_pk_f32_fp8_e32 v[78:79], v76
	v_cvt_pk_f32_fp8_sdwa v[76:77], v77 src0_sel:WORD_1
	v_pk_fma_f32 v[74:75], v[78:79], v[202:203], v[74:75]
	s_nop 0
	v_pk_fma_f32 v[74:75], v[80:81], v[138:139], v[74:75]
	v_pk_fma_f32 v[74:75], v[82:83], v[142:143], v[74:75]
	v_pk_fma_f32 v[74:75], v[76:77], v[140:141], v[74:75]
	v_add_f32_e32 v74, v74, v75
	s_nop 1
	v_add_f32_dpp v75, v167, v167 row_shl:4 row_mask:0xf bank_mask:0x5
	v_add_f32_dpp v75, v108, v108 row_shr:4 row_mask:0xf bank_mask:0xa
	v_add_f32_dpp v76, v136, v136 row_shl:4 row_mask:0xf bank_mask:0x5
	v_add_f32_dpp v76, v104, v104 row_shr:4 row_mask:0xf bank_mask:0xa
	v_add_f32_dpp v77, v132, v132 row_shl:4 row_mask:0xf bank_mask:0x5
	v_add_f32_dpp v77, v100, v100 row_shr:4 row_mask:0xf bank_mask:0xa
	v_add_f32_dpp v78, v128, v128 row_shl:4 row_mask:0xf bank_mask:0x5
	v_add_f32_dpp v78, v96, v96 row_shr:4 row_mask:0xf bank_mask:0xa
	v_add_f32_dpp v79, v124, v124 row_shl:4 row_mask:0xf bank_mask:0x5
	v_add_f32_dpp v79, v92, v92 row_shr:4 row_mask:0xf bank_mask:0xa
	v_add_f32_dpp v80, v120, v120 row_shl:4 row_mask:0xf bank_mask:0x5
	v_add_f32_dpp v80, v88, v88 row_shr:4 row_mask:0xf bank_mask:0xa
	v_add_f32_dpp v81, v116, v116 row_shl:4 row_mask:0xf bank_mask:0x5
	v_add_f32_dpp v81, v84, v84 row_shr:4 row_mask:0xf bank_mask:0xa
	v_add_f32_dpp v74, v74, v74 row_shr:4 row_mask:0xf bank_mask:0xa
	v_add_f32_dpp v74, v112, v112 row_shl:4 row_mask:0xf bank_mask:0x5
	s_nop 1
	v_add_f32_dpp v75, v75, v75 quad_perm:[2,3,0,1] row_mask:0xf bank_mask:0xf
	v_add_f32_dpp v79, v79, v79 quad_perm:[2,3,0,1] row_mask:0xf bank_mask:0xf
	v_cndmask_b32_e64 v75, v79, v75, s[12:13]
	v_add_f32_dpp v77, v77, v77 quad_perm:[2,3,0,1] row_mask:0xf bank_mask:0xf
	v_add_f32_dpp v81, v81, v81 quad_perm:[2,3,0,1] row_mask:0xf bank_mask:0xf
	v_cndmask_b32_e64 v77, v81, v77, s[12:13]
	v_add_f32_dpp v76, v76, v76 quad_perm:[2,3,0,1] row_mask:0xf bank_mask:0xf
	v_add_f32_dpp v80, v80, v80 quad_perm:[2,3,0,1] row_mask:0xf bank_mask:0xf
	v_cndmask_b32_e64 v76, v80, v76, s[12:13]
	v_add_f32_dpp v78, v78, v78 quad_perm:[2,3,0,1] row_mask:0xf bank_mask:0xf
	v_add_f32_dpp v74, v74, v74 quad_perm:[2,3,0,1] row_mask:0xf bank_mask:0xf
	v_cndmask_b32_e64 v74, v74, v78, s[12:13]
	s_nop 1
	v_add_f32_dpp v75, v75, v75 quad_perm:[1,0,3,2] row_mask:0xf bank_mask:0xf
	v_add_f32_dpp v77, v77, v77 quad_perm:[1,0,3,2] row_mask:0xf bank_mask:0xf
	v_cndmask_b32_e64 v75, v77, v75, s[14:15]
	v_add_f32_dpp v76, v76, v76 quad_perm:[1,0,3,2] row_mask:0xf bank_mask:0xf
	v_add_f32_dpp v74, v74, v74 quad_perm:[1,0,3,2] row_mask:0xf bank_mask:0xf
	v_cndmask_b32_e64 v74, v74, v76, s[14:15]
	global_store_dword v[200:201], v75, off
	global_store_dword v[200:201], v74, off offset:32
	v_lshl_add_u64 v[198:199], v[198:199], 0, s[40:41]
	v_add_u32_e32 v165, 0x400, v165
	v_lshl_add_u64 v[200:201], v[200:201], 0, s[42:43]
	s_and_b64 vcc, exec, s[28:29]
	s_cbranch_vccnz .LBB0_681
; DI float bflo(u32 u) { return __uint_as_float(u << 16); }
; DI float bfhi(u32 u) { return __uint_as_float(u & 0xffff0000u); }
; DI void dn2_issue(u32x4 (&W)[16], const int* pl, const unsigned char* wbase, int grp) {
; #pragma unroll
;   for (int j = 0; j < 16; ++j) W[j] = *(const u32x4*)(wbase + (size_t)pl[8 * j + grp] * 1024);
; }
; DI void dn2_math(const u32x4 (&W)[16], u32x4 x0, u32x4 x1, float* __restrict__ parow, int lane) {
;   f2 xf[8];
; #pragma unroll
;   for (int q = 0; q < 4; ++q) { xf[q] = f2{bflo(x0[q]), bfhi(x0[q])}; xf[4 + q] = f2{bflo(x1[q]), bfhi(x1[q])}; }
;   float pv[16];
; #pragma unroll
;   for (int j = 0; j < 16; ++j) {
;     f2 s2 = {0.f, 0.f};
; #pragma unroll
;     for (int d = 0; d < 4; ++d) {
;       f2 lo = __builtin_amdgcn_cvt_pk_f32_fp8((int)W[j][d], false);
;       f2 hi = __builtin_amdgcn_cvt_pk_f32_fp8((int)W[j][d], true);
;       s2 = lo * xf[2 * d] + s2;
;       s2 = hi * xf[2 * d + 1] + s2;
;     }
;     pv[j] = s2.x + s2.y;
;   }
.LBB0_694:
	ds_read2_b32 v[134:135], v165 offset1:8
	ds_read2_b32 v[126:127], v165 offset0:16 offset1:24
	ds_read2_b32 v[118:119], v165 offset0:32 offset1:40
	ds_read2_b32 v[110:111], v165 offset0:48 offset1:56
	ds_read2_b32 v[102:103], v165 offset0:64 offset1:72
	ds_read2_b32 v[94:95], v165 offset0:80 offset1:88
	ds_read2_b32 v[86:87], v165 offset0:96 offset1:104
	ds_read2_b32 v[78:79], v165 offset0:112 offset1:120
	s_waitcnt lgkmcnt(7)
	v_lshl_add_u32 v130, v135, 10, v250
	v_lshl_add_u32 v134, v134, 10, v250
	global_load_dwordx4 v[134:137], v134, s[98:99]
	global_load_dwordx4 v[130:133], v130, s[98:99]
	s_waitcnt lgkmcnt(6)
	v_lshl_add_u32 v122, v127, 10, v250
	v_lshl_add_u32 v126, v126, 10, v250
	global_load_dwordx4 v[126:129], v126, s[98:99]
	global_load_dwordx4 v[122:125], v122, s[98:99]
	s_waitcnt lgkmcnt(5)
	v_lshl_add_u32 v114, v119, 10, v250
	v_lshl_add_u32 v118, v118, 10, v250
	global_load_dwordx4 v[118:121], v118, s[98:99]
	global_load_dwordx4 v[114:117], v114, s[98:99]
	s_waitcnt lgkmcnt(4)
	v_lshl_add_u32 v106, v111, 10, v250
	v_lshl_add_u32 v110, v110, 10, v250
	global_load_dwordx4 v[110:113], v110, s[98:99]
	global_load_dwordx4 v[106:109], v106, s[98:99]
	s_waitcnt lgkmcnt(3)
	v_lshl_add_u32 v98, v103, 10, v250
	v_lshl_add_u32 v102, v102, 10, v250
	global_load_dwordx4 v[102:105], v102, s[98:99]
	global_load_dwordx4 v[98:101], v98, s[98:99]
	s_waitcnt lgkmcnt(2)
	v_lshl_add_u32 v90, v95, 10, v250
	v_lshl_add_u32 v94, v94, 10, v250
	global_load_dwordx4 v[94:97], v94, s[98:99]
	global_load_dwordx4 v[90:93], v90, s[98:99]
	s_waitcnt lgkmcnt(1)
	v_lshl_add_u32 v82, v87, 10, v250
	v_lshl_add_u32 v86, v86, 10, v250
	global_load_dwordx4 v[86:89], v86, s[98:99]
	global_load_dwordx4 v[82:85], v82, s[98:99]
	s_waitcnt lgkmcnt(0)
	v_lshl_add_u32 v74, v79, 10, v250
	v_lshl_add_u32 v78, v78, 10, v250
	global_load_dwordx4 v[78:81], v78, s[98:99]
	global_load_dwordx4 v[74:77], v74, s[98:99]
	s_nop 0
	global_load_dwordx4 v[138:141], v[198:199], off offset:-2032
	global_load_dwordx4 v[142:145], v[198:199], off offset:-2048
	s_waitcnt vmcnt(35)
	v_cvt_pk_f32_fp8_e32 v[230:231], v2
	v_cvt_pk_f32_fp8_sdwa v[232:233], v2 src0_sel:WORD_1
	v_cvt_pk_f32_fp8_e32 v[234:235], v3
	s_waitcnt vmcnt(18)
	v_lshlrev_b32_e32 v210, 16, v70
	v_and_b32_e32 v211, 0xffff0000, v70
	v_cvt_pk_f32_fp8_sdwa v[236:237], v3 src0_sel:WORD_1
	v_lshlrev_b32_e32 v212, 16, v71
	v_and_b32_e32 v213, 0xffff0000, v71
	v_pk_fma_f32 v[230:231], v[230:231], v[210:211], 0 op_sel_hi:[1,1,0]
	v_lshlrev_b32_e32 v214, 16, v72
	v_and_b32_e32 v215, 0xffff0000, v72
	v_pk_fma_f32 v[230:231], v[232:233], v[212:213], v[230:231]
	v_cvt_pk_f32_fp8_e32 v[232:233], v4
	v_lshlrev_b32_e32 v216, 16, v73
	v_and_b32_e32 v217, 0xffff0000, v73
	v_pk_fma_f32 v[230:231], v[234:235], v[214:215], v[230:231]
	v_cvt_pk_f32_fp8_sdwa v[234:235], v4 src0_sel:WORD_1
	v_pk_fma_f32 v[230:231], v[236:237], v[216:217], v[230:231]
	v_cvt_pk_f32_fp8_e32 v[236:237], v5
	v_lshlrev_b32_e32 v202, 16, v66
	v_and_b32_e32 v203, 0xffff0000, v66
	v_cvt_pk_f32_fp8_sdwa v[238:239], v5 src0_sel:WORD_1
	v_lshlrev_b32_e32 v204, 16, v67
	v_and_b32_e32 v205, 0xffff0000, v67
	v_pk_fma_f32 v[230:231], v[232:233], v[202:203], v[230:231]
	v_lshlrev_b32_e32 v206, 16, v68
	v_and_b32_e32 v207, 0xffff0000, v68
	v_pk_fma_f32 v[230:231], v[234:235], v[204:205], v[230:231]
	v_lshlrev_b32_e32 v208, 16, v69
	v_and_b32_e32 v209, 0xffff0000, v69
	v_pk_fma_f32 v[230:231], v[236:237], v[206:207], v[230:231]
	v_cvt_pk_f32_fp8_sdwa v[232:233], v6 src0_sel:WORD_1
	v_pk_fma_f32 v[230:231], v[238:239], v[208:209], v[230:231]
	v_cvt_pk_f32_fp8_e32 v[234:235], v7
	v_add_f32_e32 v167, v230, v231
	v_cvt_pk_f32_fp8_e32 v[230:231], v6
	v_cvt_pk_f32_fp8_sdwa v[236:237], v7 src0_sel:WORD_1
	v_cvt_pk_f32_fp8_sdwa v[238:239], v9 src0_sel:WORD_1
	v_pk_fma_f32 v[230:231], v[230:231], v[210:211], 0 op_sel_hi:[1,1,0]
	s_nop 0
	v_pk_fma_f32 v[230:231], v[232:233], v[212:213], v[230:231]
	v_cvt_pk_f32_fp8_e32 v[232:233], v8
	v_pk_fma_f32 v[230:231], v[234:235], v[214:215], v[230:231]
	v_cvt_pk_f32_fp8_sdwa v[234:235], v8 src0_sel:WORD_1
	v_pk_fma_f32 v[230:231], v[236:237], v[216:217], v[230:231]
	v_cvt_pk_f32_fp8_e32 v[236:237], v9
	v_pk_fma_f32 v[230:231], v[232:233], v[202:203], v[230:231]
	v_cvt_pk_f32_fp8_sdwa v[232:233], v10 src0_sel:WORD_1
	v_pk_fma_f32 v[230:231], v[234:235], v[204:205], v[230:231]
	v_cvt_pk_f32_fp8_e32 v[234:235], v11
	v_pk_fma_f32 v[230:231], v[236:237], v[206:207], v[230:231]
	v_cvt_pk_f32_fp8_sdwa v[236:237], v11 src0_sel:WORD_1
	v_pk_fma_f32 v[230:231], v[238:239], v[208:209], v[230:231]
	v_cvt_pk_f32_fp8_sdwa v[238:239], v13 src0_sel:WORD_1
	v_add_f32_e32 v169, v230, v231
	v_cvt_pk_f32_fp8_e32 v[230:231], v10
	v_pk_fma_f32 v[230:231], v[230:231], v[210:211], 0 op_sel_hi:[1,1,0]
	s_nop 0
	v_pk_fma_f32 v[230:231], v[232:233], v[212:213], v[230:231]
	v_cvt_pk_f32_fp8_e32 v[232:233], v12
	v_pk_fma_f32 v[230:231], v[234:235], v[214:215], v[230:231]
	v_cvt_pk_f32_fp8_sdwa v[234:235], v12 src0_sel:WORD_1
	v_pk_fma_f32 v[230:231], v[236:237], v[216:217], v[230:231]
	v_cvt_pk_f32_fp8_e32 v[236:237], v13
	v_pk_fma_f32 v[230:231], v[232:233], v[202:203], v[230:231]
	v_cvt_pk_f32_fp8_sdwa v[232:233], v14 src0_sel:WORD_1
	v_pk_fma_f32 v[230:231], v[234:235], v[204:205], v[230:231]
	v_cvt_pk_f32_fp8_e32 v[234:235], v15
	v_pk_fma_f32 v[230:231], v[236:237], v[206:207], v[230:231]
	v_cvt_pk_f32_fp8_sdwa v[236:237], v15 src0_sel:WORD_1
	v_pk_fma_f32 v[230:231], v[238:239], v[208:209], v[230:231]
	v_cvt_pk_f32_fp8_sdwa v[238:239], v17 src0_sel:WORD_1
	v_add_f32_e32 v171, v230, v231
	v_cvt_pk_f32_fp8_e32 v[230:231], v14
	v_pk_fma_f32 v[230:231], v[230:231], v[210:211], 0 op_sel_hi:[1,1,0]
; DI void dn2_math(const u32x4 (&W)[16], u32x4 x0, u32x4 x1, float* __restrict__ parow, int lane) {
;     ...
;   for (int j = 0; j < 16; ++j) {
;     f2 s2 = {0.f, 0.f};
; #pragma unroll
;     for (int d = 0; d < 4; ++d) {
;       f2 lo = __builtin_amdgcn_cvt_pk_f32_fp8((int)W[j][d], false);
;       f2 hi = __builtin_amdgcn_cvt_pk_f32_fp8((int)W[j][d], true);
;       s2 = lo * xf[2 * d] + s2;
;       s2 = hi * xf[2 * d + 1] + s2;
;     }
;     pv[j] = s2.x + s2.y;
;   }
	s_nop 0
	v_pk_fma_f32 v[230:231], v[232:233], v[212:213], v[230:231]
	v_cvt_pk_f32_fp8_e32 v[232:233], v16
	v_pk_fma_f32 v[230:231], v[234:235], v[214:215], v[230:231]
	v_cvt_pk_f32_fp8_sdwa v[234:235], v16 src0_sel:WORD_1
	v_pk_fma_f32 v[230:231], v[236:237], v[216:217], v[230:231]
	v_cvt_pk_f32_fp8_e32 v[236:237], v17
	v_pk_fma_f32 v[230:231], v[232:233], v[202:203], v[230:231]
	v_cvt_pk_f32_fp8_sdwa v[232:233], v18 src0_sel:WORD_1
	v_pk_fma_f32 v[230:231], v[234:235], v[204:205], v[230:231]
	v_cvt_pk_f32_fp8_e32 v[234:235], v19
	v_pk_fma_f32 v[230:231], v[236:237], v[206:207], v[230:231]
	v_cvt_pk_f32_fp8_sdwa v[236:237], v19 src0_sel:WORD_1
	v_pk_fma_f32 v[230:231], v[238:239], v[208:209], v[230:231]
	v_cvt_pk_f32_fp8_sdwa v[238:239], v21 src0_sel:WORD_1
	v_add_f32_e32 v173, v230, v231
	v_cvt_pk_f32_fp8_e32 v[230:231], v18
	v_pk_fma_f32 v[230:231], v[230:231], v[210:211], 0 op_sel_hi:[1,1,0]
	s_nop 0
	v_pk_fma_f32 v[230:231], v[232:233], v[212:213], v[230:231]
	v_cvt_pk_f32_fp8_e32 v[232:233], v20
	v_pk_fma_f32 v[230:231], v[234:235], v[214:215], v[230:231]
	v_cvt_pk_f32_fp8_sdwa v[234:235], v20 src0_sel:WORD_1
	v_pk_fma_f32 v[230:231], v[236:237], v[216:217], v[230:231]
	v_cvt_pk_f32_fp8_e32 v[236:237], v21
	v_pk_fma_f32 v[230:231], v[232:233], v[202:203], v[230:231]
	v_cvt_pk_f32_fp8_sdwa v[232:233], v22 src0_sel:WORD_1
	v_pk_fma_f32 v[230:231], v[234:235], v[204:205], v[230:231]
	v_cvt_pk_f32_fp8_e32 v[234:235], v23
	v_pk_fma_f32 v[230:231], v[236:237], v[206:207], v[230:231]
	v_cvt_pk_f32_fp8_sdwa v[236:237], v23 src0_sel:WORD_1
	v_pk_fma_f32 v[230:231], v[238:239], v[208:209], v[230:231]
	v_cvt_pk_f32_fp8_sdwa v[238:239], v25 src0_sel:WORD_1
	v_add_f32_e32 v175, v230, v231
	v_cvt_pk_f32_fp8_e32 v[230:231], v22
	v_pk_fma_f32 v[230:231], v[230:231], v[210:211], 0 op_sel_hi:[1,1,0]
	s_nop 0
	v_pk_fma_f32 v[230:231], v[232:233], v[212:213], v[230:231]
	v_cvt_pk_f32_fp8_e32 v[232:233], v24
	v_pk_fma_f32 v[230:231], v[234:235], v[214:215], v[230:231]
	v_cvt_pk_f32_fp8_sdwa v[234:235], v24 src0_sel:WORD_1
	v_pk_fma_f32 v[230:231], v[236:237], v[216:217], v[230:231]
	v_cvt_pk_f32_fp8_e32 v[236:237], v25
	v_pk_fma_f32 v[230:231], v[232:233], v[202:203], v[230:231]
	v_cvt_pk_f32_fp8_sdwa v[232:233], v26 src0_sel:WORD_1
	v_pk_fma_f32 v[230:231], v[234:235], v[204:205], v[230:231]
	v_cvt_pk_f32_fp8_e32 v[234:235], v27
	v_pk_fma_f32 v[230:231], v[236:237], v[206:207], v[230:231]
	v_cvt_pk_f32_fp8_sdwa v[236:237], v27 src0_sel:WORD_1
	v_pk_fma_f32 v[230:231], v[238:239], v[208:209], v[230:231]
	v_cvt_pk_f32_fp8_sdwa v[238:239], v29 src0_sel:WORD_1
	v_add_f32_e32 v177, v230, v231
	v_cvt_pk_f32_fp8_e32 v[230:231], v26
	v_pk_fma_f32 v[230:231], v[230:231], v[210:211], 0 op_sel_hi:[1,1,0]
	s_nop 0
	v_pk_fma_f32 v[230:231], v[232:233], v[212:213], v[230:231]
	v_cvt_pk_f32_fp8_e32 v[232:233], v28
	v_pk_fma_f32 v[230:231], v[234:235], v[214:215], v[230:231]
	v_cvt_pk_f32_fp8_sdwa v[234:235], v28 src0_sel:WORD_1
	v_pk_fma_f32 v[230:231], v[236:237], v[216:217], v[230:231]
	v_cvt_pk_f32_fp8_e32 v[236:237], v29
	v_pk_fma_f32 v[230:231], v[232:233], v[202:203], v[230:231]
	v_cvt_pk_f32_fp8_sdwa v[232:233], v30 src0_sel:WORD_1
	v_pk_fma_f32 v[230:231], v[234:235], v[204:205], v[230:231]
	v_cvt_pk_f32_fp8_e32 v[234:235], v31
	v_pk_fma_f32 v[230:231], v[236:237], v[206:207], v[230:231]
	v_cvt_pk_f32_fp8_sdwa v[236:237], v31 src0_sel:WORD_1
	v_pk_fma_f32 v[230:231], v[238:239], v[208:209], v[230:231]
	v_cvt_pk_f32_fp8_sdwa v[238:239], v33 src0_sel:WORD_1
	v_add_f32_e32 v179, v230, v231
	v_cvt_pk_f32_fp8_e32 v[230:231], v30
	v_pk_fma_f32 v[230:231], v[230:231], v[210:211], 0 op_sel_hi:[1,1,0]
	s_nop 0
	v_pk_fma_f32 v[230:231], v[232:233], v[212:213], v[230:231]
	v_cvt_pk_f32_fp8_e32 v[232:233], v32
	v_pk_fma_f32 v[230:231], v[234:235], v[214:215], v[230:231]
	v_cvt_pk_f32_fp8_sdwa v[234:235], v32 src0_sel:WORD_1
	v_pk_fma_f32 v[230:231], v[236:237], v[216:217], v[230:231]
	v_cvt_pk_f32_fp8_e32 v[236:237], v33
	v_pk_fma_f32 v[230:231], v[232:233], v[202:203], v[230:231]
	v_cvt_pk_f32_fp8_sdwa v[232:233], v34 src0_sel:WORD_1
	v_pk_fma_f32 v[230:231], v[234:235], v[204:205], v[230:231]
	v_cvt_pk_f32_fp8_e32 v[234:235], v35
	v_pk_fma_f32 v[230:231], v[236:237], v[206:207], v[230:231]
	v_cvt_pk_f32_fp8_sdwa v[236:237], v35 src0_sel:WORD_1
	v_pk_fma_f32 v[230:231], v[238:239], v[208:209], v[230:231]
	v_cvt_pk_f32_fp8_sdwa v[238:239], v37 src0_sel:WORD_1
	v_add_f32_e32 v181, v230, v231
	v_cvt_pk_f32_fp8_e32 v[230:231], v34
	v_pk_fma_f32 v[230:231], v[230:231], v[210:211], 0 op_sel_hi:[1,1,0]
	s_nop 0
	v_pk_fma_f32 v[230:231], v[232:233], v[212:213], v[230:231]
	v_cvt_pk_f32_fp8_e32 v[232:233], v36
	v_pk_fma_f32 v[230:231], v[234:235], v[214:215], v[230:231]
	v_cvt_pk_f32_fp8_sdwa v[234:235], v36 src0_sel:WORD_1
	v_pk_fma_f32 v[230:231], v[236:237], v[216:217], v[230:231]
	v_cvt_pk_f32_fp8_e32 v[236:237], v37
	v_pk_fma_f32 v[230:231], v[232:233], v[202:203], v[230:231]
	v_cvt_pk_f32_fp8_sdwa v[232:233], v38 src0_sel:WORD_1
	v_pk_fma_f32 v[230:231], v[234:235], v[204:205], v[230:231]
	v_cvt_pk_f32_fp8_e32 v[234:235], v39
	v_pk_fma_f32 v[230:231], v[236:237], v[206:207], v[230:231]
	v_cvt_pk_f32_fp8_sdwa v[236:237], v39 src0_sel:WORD_1
	v_pk_fma_f32 v[230:231], v[238:239], v[208:209], v[230:231]
	v_cvt_pk_f32_fp8_sdwa v[238:239], v41 src0_sel:WORD_1
	v_add_f32_e32 v183, v230, v231
	v_cvt_pk_f32_fp8_e32 v[230:231], v38
	v_pk_fma_f32 v[230:231], v[230:231], v[210:211], 0 op_sel_hi:[1,1,0]
	s_nop 0
	v_pk_fma_f32 v[230:231], v[232:233], v[212:213], v[230:231]
	v_cvt_pk_f32_fp8_e32 v[232:233], v40
	v_pk_fma_f32 v[230:231], v[234:235], v[214:215], v[230:231]
; DI void dn2_math(const u32x4 (&W)[16], u32x4 x0, u32x4 x1, float* __restrict__ parow, int lane) {
;     ...
;   for (int j = 0; j < 16; ++j) {
;     f2 s2 = {0.f, 0.f};
; #pragma unroll
;     for (int d = 0; d < 4; ++d) {
;       f2 lo = __builtin_amdgcn_cvt_pk_f32_fp8((int)W[j][d], false);
;       f2 hi = __builtin_amdgcn_cvt_pk_f32_fp8((int)W[j][d], true);
;       s2 = lo * xf[2 * d] + s2;
;       s2 = hi * xf[2 * d + 1] + s2;
;     }
;     pv[j] = s2.x + s2.y;
;   }
	v_cvt_pk_f32_fp8_sdwa v[234:235], v40 src0_sel:WORD_1
	v_pk_fma_f32 v[230:231], v[236:237], v[216:217], v[230:231]
	v_cvt_pk_f32_fp8_e32 v[236:237], v41
	v_pk_fma_f32 v[230:231], v[232:233], v[202:203], v[230:231]
	v_cvt_pk_f32_fp8_sdwa v[232:233], v42 src0_sel:WORD_1
	v_pk_fma_f32 v[230:231], v[234:235], v[204:205], v[230:231]
	v_cvt_pk_f32_fp8_e32 v[234:235], v43
	v_pk_fma_f32 v[230:231], v[236:237], v[206:207], v[230:231]
	v_cvt_pk_f32_fp8_sdwa v[236:237], v43 src0_sel:WORD_1
	v_pk_fma_f32 v[230:231], v[238:239], v[208:209], v[230:231]
	v_cvt_pk_f32_fp8_sdwa v[238:239], v45 src0_sel:WORD_1
	v_add_f32_e32 v185, v230, v231
	v_cvt_pk_f32_fp8_e32 v[230:231], v42
	v_pk_fma_f32 v[230:231], v[230:231], v[210:211], 0 op_sel_hi:[1,1,0]
	s_nop 0
	v_pk_fma_f32 v[230:231], v[232:233], v[212:213], v[230:231]
	v_cvt_pk_f32_fp8_e32 v[232:233], v44
	v_pk_fma_f32 v[230:231], v[234:235], v[214:215], v[230:231]
	v_cvt_pk_f32_fp8_sdwa v[234:235], v44 src0_sel:WORD_1
	v_pk_fma_f32 v[230:231], v[236:237], v[216:217], v[230:231]
	v_cvt_pk_f32_fp8_e32 v[236:237], v45
	v_pk_fma_f32 v[230:231], v[232:233], v[202:203], v[230:231]
	v_cvt_pk_f32_fp8_sdwa v[232:233], v46 src0_sel:WORD_1
	v_pk_fma_f32 v[230:231], v[234:235], v[204:205], v[230:231]
	v_cvt_pk_f32_fp8_e32 v[234:235], v47
	v_pk_fma_f32 v[230:231], v[236:237], v[206:207], v[230:231]
	v_cvt_pk_f32_fp8_sdwa v[236:237], v47 src0_sel:WORD_1
	v_pk_fma_f32 v[230:231], v[238:239], v[208:209], v[230:231]
	v_cvt_pk_f32_fp8_sdwa v[238:239], v49 src0_sel:WORD_1
	v_add_f32_e32 v187, v230, v231
	v_cvt_pk_f32_fp8_e32 v[230:231], v46
	v_pk_fma_f32 v[230:231], v[230:231], v[210:211], 0 op_sel_hi:[1,1,0]
	s_nop 0
	v_pk_fma_f32 v[230:231], v[232:233], v[212:213], v[230:231]
	v_cvt_pk_f32_fp8_e32 v[232:233], v48
	v_pk_fma_f32 v[230:231], v[234:235], v[214:215], v[230:231]
	v_cvt_pk_f32_fp8_sdwa v[234:235], v48 src0_sel:WORD_1
	v_pk_fma_f32 v[230:231], v[236:237], v[216:217], v[230:231]
	v_cvt_pk_f32_fp8_e32 v[236:237], v49
	v_pk_fma_f32 v[230:231], v[232:233], v[202:203], v[230:231]
	v_cvt_pk_f32_fp8_sdwa v[232:233], v50 src0_sel:WORD_1
	v_pk_fma_f32 v[230:231], v[234:235], v[204:205], v[230:231]
	v_cvt_pk_f32_fp8_e32 v[234:235], v51
	v_pk_fma_f32 v[230:231], v[236:237], v[206:207], v[230:231]
	v_cvt_pk_f32_fp8_sdwa v[236:237], v51 src0_sel:WORD_1
	v_pk_fma_f32 v[230:231], v[238:239], v[208:209], v[230:231]
	v_cvt_pk_f32_fp8_sdwa v[238:239], v53 src0_sel:WORD_1
	v_add_f32_e32 v189, v230, v231
	v_cvt_pk_f32_fp8_e32 v[230:231], v50
	v_pk_fma_f32 v[230:231], v[230:231], v[210:211], 0 op_sel_hi:[1,1,0]
	s_nop 0
	v_pk_fma_f32 v[230:231], v[232:233], v[212:213], v[230:231]
	v_cvt_pk_f32_fp8_e32 v[232:233], v52
	v_pk_fma_f32 v[230:231], v[234:235], v[214:215], v[230:231]
	v_cvt_pk_f32_fp8_sdwa v[234:235], v52 src0_sel:WORD_1
	v_pk_fma_f32 v[230:231], v[236:237], v[216:217], v[230:231]
	v_cvt_pk_f32_fp8_e32 v[236:237], v53
	v_pk_fma_f32 v[230:231], v[232:233], v[202:203], v[230:231]
	v_cvt_pk_f32_fp8_sdwa v[232:233], v54 src0_sel:WORD_1
	v_pk_fma_f32 v[230:231], v[234:235], v[204:205], v[230:231]
	v_cvt_pk_f32_fp8_e32 v[234:235], v55
	v_pk_fma_f32 v[230:231], v[236:237], v[206:207], v[230:231]
	v_cvt_pk_f32_fp8_sdwa v[236:237], v55 src0_sel:WORD_1
	v_pk_fma_f32 v[230:231], v[238:239], v[208:209], v[230:231]
	v_cvt_pk_f32_fp8_sdwa v[238:239], v57 src0_sel:WORD_1
	v_add_f32_e32 v240, v230, v231
	v_cvt_pk_f32_fp8_e32 v[230:231], v54
	v_pk_fma_f32 v[230:231], v[230:231], v[210:211], 0 op_sel_hi:[1,1,0]
	s_nop 0
	v_pk_fma_f32 v[230:231], v[232:233], v[212:213], v[230:231]
	v_cvt_pk_f32_fp8_e32 v[232:233], v56
	v_pk_fma_f32 v[230:231], v[234:235], v[214:215], v[230:231]
	v_cvt_pk_f32_fp8_sdwa v[234:235], v56 src0_sel:WORD_1
	v_pk_fma_f32 v[230:231], v[236:237], v[216:217], v[230:231]
	v_cvt_pk_f32_fp8_e32 v[236:237], v57
	v_pk_fma_f32 v[230:231], v[232:233], v[202:203], v[230:231]
	v_cvt_pk_f32_fp8_sdwa v[232:233], v58 src0_sel:WORD_1
	v_pk_fma_f32 v[230:231], v[234:235], v[204:205], v[230:231]
	v_cvt_pk_f32_fp8_e32 v[234:235], v59
	v_pk_fma_f32 v[230:231], v[236:237], v[206:207], v[230:231]
	v_cvt_pk_f32_fp8_sdwa v[236:237], v59 src0_sel:WORD_1
	v_pk_fma_f32 v[230:231], v[238:239], v[208:209], v[230:231]
	v_cvt_pk_f32_fp8_sdwa v[238:239], v61 src0_sel:WORD_1
	v_add_f32_e32 v241, v230, v231
	v_cvt_pk_f32_fp8_e32 v[230:231], v58
	v_pk_fma_f32 v[230:231], v[230:231], v[210:211], 0 op_sel_hi:[1,1,0]
	s_nop 0
	v_pk_fma_f32 v[230:231], v[232:233], v[212:213], v[230:231]
	v_cvt_pk_f32_fp8_e32 v[232:233], v60
	v_pk_fma_f32 v[230:231], v[234:235], v[214:215], v[230:231]
	v_cvt_pk_f32_fp8_sdwa v[234:235], v60 src0_sel:WORD_1
	v_pk_fma_f32 v[230:231], v[236:237], v[216:217], v[230:231]
	v_cvt_pk_f32_fp8_e32 v[236:237], v61
	v_pk_fma_f32 v[230:231], v[232:233], v[202:203], v[230:231]
	v_cvt_pk_f32_fp8_sdwa v[232:233], v62 src0_sel:WORD_1
	v_pk_fma_f32 v[230:231], v[234:235], v[204:205], v[230:231]
	v_cvt_pk_f32_fp8_e32 v[234:235], v63
	v_pk_fma_f32 v[230:231], v[236:237], v[206:207], v[230:231]
	v_cvt_pk_f32_fp8_sdwa v[236:237], v63 src0_sel:WORD_1
	v_pk_fma_f32 v[230:231], v[238:239], v[208:209], v[230:231]
	s_nop 0
	v_add_f32_e32 v238, v230, v231
	v_cvt_pk_f32_fp8_e32 v[230:231], v62
	v_pk_fma_f32 v[210:211], v[230:231], v[210:211], 0 op_sel_hi:[1,1,0]
; DI void dn2_issue(u32x4 (&W)[16], const int* pl, const unsigned char* wbase, int grp) {
; #pragma unroll
;   for (int j = 0; j < 16; ++j) W[j] = *(const u32x4*)(wbase + (size_t)pl[8 * j + grp] * 1024);
; }
; DI void dn2_math(const u32x4 (&W)[16], u32x4 x0, u32x4 x1, float* __restrict__ parow, int lane) {
;     ...
;   for (int j = 0; j < 16; ++j) {
;     f2 s2 = {0.f, 0.f};
; #pragma unroll
;     for (int d = 0; d < 4; ++d) {
;       f2 lo = __builtin_amdgcn_cvt_pk_f32_fp8((int)W[j][d], false);
;       f2 hi = __builtin_amdgcn_cvt_pk_f32_fp8((int)W[j][d], true);
;       s2 = lo * xf[2 * d] + s2;
;       s2 = hi * xf[2 * d + 1] + s2;
;     }
;     pv[j] = s2.x + s2.y;
;   }
;   const bool b2 = lane & 4, b1 = lane & 2, b0 = lane & 1;
;   float q8[8];
; #pragma unroll
;   for (int i = 0; i < 8; ++i) { float snd = b2 ? pv[i] : pv[i + 8]; float kp = b2 ? pv[i + 8] : pv[i]; q8[i] = kp + __shfl_xor(snd, 4); }
;   float q4[4];
; #pragma unroll
;   for (int i = 0; i < 4; ++i) { float snd = b1 ? q8[i] : q8[i + 4]; float kp = b1 ? q8[i + 4] : q8[i]; q4[i] = kp + __shfl_xor(snd, 2); }
;   float r2[2];
; #pragma unroll
;   for (int i = 0; i < 2; ++i) { float snd = b0 ? q4[i] : q4[i + 2]; float kp = b0 ? q4[i + 2] : q4[i]; r2[i] = kp + __shfl_xor(snd, 1); }
;   const int j0 = (b0 ? 2 : 0) + (b1 ? 4 : 0) + (b2 ? 8 : 0);
;   const int grp = lane >> 3;
;   parow[8 * j0 + grp] = r2[0];
;   parow[8 * (j0 + 1) + grp] = r2[1];
	s_nop 0
	v_pk_fma_f32 v[210:211], v[232:233], v[212:213], v[210:211]
	v_cvt_pk_f32_fp8_e32 v[212:213], v64
	v_pk_fma_f32 v[210:211], v[234:235], v[214:215], v[210:211]
	v_cvt_pk_f32_fp8_sdwa v[214:215], v64 src0_sel:WORD_1
	v_pk_fma_f32 v[210:211], v[236:237], v[216:217], v[210:211]
	v_cvt_pk_f32_fp8_e32 v[216:217], v65
	v_cvt_pk_f32_fp8_sdwa v[230:231], v65 src0_sel:WORD_1
	v_pk_fma_f32 v[202:203], v[212:213], v[202:203], v[210:211]
	s_nop 0
	v_pk_fma_f32 v[202:203], v[214:215], v[204:205], v[202:203]
	v_pk_fma_f32 v[202:203], v[216:217], v[206:207], v[202:203]
	v_pk_fma_f32 v[202:203], v[230:231], v[208:209], v[202:203]
	v_add_f32_e32 v202, v202, v203
	s_nop 1
	v_add_f32_dpp v167, v167, v167 row_shl:4 row_mask:0xf bank_mask:0x5
	v_add_f32_dpp v167, v183, v183 row_shr:4 row_mask:0xf bank_mask:0xa
	v_add_f32_dpp v173, v173, v173 row_shl:4 row_mask:0xf bank_mask:0x5
	v_add_f32_dpp v173, v189, v189 row_shr:4 row_mask:0xf bank_mask:0xa
	v_add_f32_dpp v175, v175, v175 row_shl:4 row_mask:0xf bank_mask:0x5
	v_add_f32_dpp v175, v240, v240 row_shr:4 row_mask:0xf bank_mask:0xa
	v_add_f32_dpp v169, v169, v169 row_shl:4 row_mask:0xf bank_mask:0x5
	v_add_f32_dpp v169, v185, v185 row_shr:4 row_mask:0xf bank_mask:0xa
	v_add_f32_dpp v171, v171, v171 row_shl:4 row_mask:0xf bank_mask:0x5
	v_add_f32_dpp v171, v187, v187 row_shr:4 row_mask:0xf bank_mask:0xa
	v_add_f32_dpp v177, v177, v177 row_shl:4 row_mask:0xf bank_mask:0x5
	v_add_f32_dpp v177, v241, v241 row_shr:4 row_mask:0xf bank_mask:0xa
	v_add_f32_dpp v179, v179, v179 row_shl:4 row_mask:0xf bank_mask:0x5
	v_add_f32_dpp v179, v238, v238 row_shr:4 row_mask:0xf bank_mask:0xa
	v_add_f32_dpp v181, v181, v181 row_shl:4 row_mask:0xf bank_mask:0x5
	v_add_f32_dpp v181, v202, v202 row_shr:4 row_mask:0xf bank_mask:0xa
	s_nop 1
	v_add_f32_dpp v167, v167, v167 quad_perm:[2,3,0,1] row_mask:0xf bank_mask:0xf
	v_add_f32_dpp v175, v175, v175 quad_perm:[2,3,0,1] row_mask:0xf bank_mask:0xf
	v_cndmask_b32_e64 v167, v175, v167, s[12:13]
	v_add_f32_dpp v171, v171, v171 quad_perm:[2,3,0,1] row_mask:0xf bank_mask:0xf
	v_add_f32_dpp v179, v179, v179 quad_perm:[2,3,0,1] row_mask:0xf bank_mask:0xf
	v_cndmask_b32_e64 v171, v179, v171, s[12:13]
	v_add_f32_dpp v169, v169, v169 quad_perm:[2,3,0,1] row_mask:0xf bank_mask:0xf
	v_add_f32_dpp v177, v177, v177 quad_perm:[2,3,0,1] row_mask:0xf bank_mask:0xf
	v_cndmask_b32_e64 v169, v177, v169, s[12:13]
	v_add_f32_dpp v173, v173, v173 quad_perm:[2,3,0,1] row_mask:0xf bank_mask:0xf
	v_add_f32_dpp v181, v181, v181 quad_perm:[2,3,0,1] row_mask:0xf bank_mask:0xf
	v_cndmask_b32_e64 v173, v181, v173, s[12:13]
	s_nop 1
	v_add_f32_dpp v167, v167, v167 quad_perm:[1,0,3,2] row_mask:0xf bank_mask:0xf
	v_add_f32_dpp v171, v171, v171 quad_perm:[1,0,3,2] row_mask:0xf bank_mask:0xf
	v_cndmask_b32_e64 v167, v171, v167, s[14:15]
	v_add_f32_dpp v169, v169, v169 quad_perm:[1,0,3,2] row_mask:0xf bank_mask:0xf
	v_add_f32_dpp v173, v173, v173 quad_perm:[1,0,3,2] row_mask:0xf bank_mask:0xf
	v_cndmask_b32_e64 v169, v173, v169, s[14:15]
	global_store_dword v[200:201], v167, off offset:-512
	global_store_dword v[200:201], v169, off offset:-480
	s_cmp_gt_u32 s46, 13
	s_cselect_b64 s[28:29], -1, 0
	s_and_b64 vcc, exec, s[28:29]
	s_cbranch_vccnz .LBB0_693
	ds_read2_b32 v[2:3], v165 offset0:128 offset1:136
	ds_read2_b32 v[10:11], v165 offset0:144 offset1:152
	ds_read2_b32 v[18:19], v165 offset0:160 offset1:168
	ds_read2_b32 v[26:27], v165 offset0:176 offset1:184
	ds_read2_b32 v[34:35], v165 offset0:192 offset1:200
	ds_read2_b32 v[42:43], v165 offset0:208 offset1:216
	ds_read2_b32 v[50:51], v165 offset0:224 offset1:232
	ds_read2_b32 v[58:59], v165 offset0:240 offset1:248
	s_waitcnt lgkmcnt(7)
	v_lshl_add_u32 v6, v3, 10, v250
	v_lshl_add_u32 v2, v2, 10, v250
	global_load_dwordx4 v[2:5], v2, s[98:99]
	global_load_dwordx4 v[6:9], v6, s[98:99]
	s_waitcnt lgkmcnt(6)
	v_lshl_add_u32 v14, v11, 10, v250
	v_lshl_add_u32 v10, v10, 10, v250
	global_load_dwordx4 v[10:13], v10, s[98:99]
	global_load_dwordx4 v[14:17], v14, s[98:99]
	s_waitcnt lgkmcnt(5)
	v_lshl_add_u32 v22, v19, 10, v250
	v_lshl_add_u32 v18, v18, 10, v250
	global_load_dwordx4 v[18:21], v18, s[98:99]
	global_load_dwordx4 v[22:25], v22, s[98:99]
	s_waitcnt lgkmcnt(4)
	v_lshl_add_u32 v30, v27, 10, v250
	v_lshl_add_u32 v26, v26, 10, v250
	global_load_dwordx4 v[26:29], v26, s[98:99]
	global_load_dwordx4 v[30:33], v30, s[98:99]
	s_waitcnt lgkmcnt(3)
	v_lshl_add_u32 v38, v35, 10, v250
	v_lshl_add_u32 v34, v34, 10, v250
	global_load_dwordx4 v[34:37], v34, s[98:99]
	global_load_dwordx4 v[38:41], v38, s[98:99]
	s_waitcnt lgkmcnt(2)
	v_lshl_add_u32 v46, v43, 10, v250
	v_lshl_add_u32 v42, v42, 10, v250
	global_load_dwordx4 v[42:45], v42, s[98:99]
	global_load_dwordx4 v[46:49], v46, s[98:99]
	s_waitcnt lgkmcnt(1)
	v_lshl_add_u32 v54, v51, 10, v250
	v_lshl_add_u32 v50, v50, 10, v250
	global_load_dwordx4 v[50:53], v50, s[98:99]
	global_load_dwordx4 v[54:57], v54, s[98:99]
	s_waitcnt lgkmcnt(0)
	v_lshl_add_u32 v62, v59, 10, v250
	v_lshl_add_u32 v58, v58, 10, v250
	global_load_dwordx4 v[58:61], v58, s[98:99]
	global_load_dwordx4 v[62:65], v62, s[98:99]
	s_nop 0
	global_load_dwordx4 v[66:69], v[198:199], off offset:16
	global_load_dwordx4 v[70:73], v[198:199], off
	s_branch .LBB0_693

; DI float bflo(u32 u) { return __uint_as_float(u << 16); }
; DI float bfhi(u32 u) { return __uint_as_float(u & 0xffff0000u); }
; DI void dn2_math(const u32x4 (&W)[16], u32x4 x0, u32x4 x1, float* __restrict__ parow, int lane) {
;   f2 xf[8];
; #pragma unroll
;   for (int q = 0; q < 4; ++q) { xf[q] = f2{bflo(x0[q]), bfhi(x0[q])}; xf[4 + q] = f2{bflo(x1[q]), bfhi(x1[q])}; }
;   float pv[16];
; #pragma unroll
;   for (int j = 0; j < 16; ++j) {
;     f2 s2 = {0.f, 0.f};
; #pragma unroll
;     for (int d = 0; d < 4; ++d) {
;       f2 lo = __builtin_amdgcn_cvt_pk_f32_fp8((int)W[j][d], false);
;       f2 hi = __builtin_amdgcn_cvt_pk_f32_fp8((int)W[j][d], true);
;       s2 = lo * xf[2 * d] + s2;
;       s2 = hi * xf[2 * d + 1] + s2;
;     }
;     pv[j] = s2.x + s2.y;
;   }
.LBB0_1516:
	s_add_i32 s40, s40, 2
	s_waitcnt vmcnt(19)
	v_cvt_pk_f32_fp8_e32 v[210:211], v134
	v_cvt_pk_f32_fp8_sdwa v[212:213], v134 src0_sel:WORD_1
	v_cvt_pk_f32_fp8_e32 v[214:215], v135
	s_waitcnt vmcnt(2)
	v_lshlrev_b32_e32 v204, 16, v142
	v_and_b32_e32 v205, 0xffff0000, v142
	v_cvt_pk_f32_fp8_sdwa v[134:135], v135 src0_sel:WORD_1
	v_lshlrev_b32_e32 v206, 16, v143
	v_and_b32_e32 v207, 0xffff0000, v143
	v_pk_fma_f32 v[210:211], v[210:211], v[204:205], 0 op_sel_hi:[1,1,0]
	v_lshlrev_b32_e32 v208, 16, v144
	v_and_b32_e32 v209, 0xffff0000, v144
	v_pk_fma_f32 v[210:211], v[212:213], v[206:207], v[210:211]
	v_lshlrev_b32_e32 v144, 16, v145
	v_and_b32_e32 v145, 0xffff0000, v145
	v_pk_fma_f32 v[210:211], v[214:215], v[208:209], v[210:211]
	v_cvt_pk_f32_fp8_sdwa v[212:213], v136 src0_sel:WORD_1
	v_pk_fma_f32 v[134:135], v[134:135], v[144:145], v[210:211]
	v_cvt_pk_f32_fp8_e32 v[210:211], v136
	v_cvt_pk_f32_fp8_e32 v[214:215], v137
	v_lshlrev_b32_e32 v202, 16, v138
	v_and_b32_e32 v203, 0xffff0000, v138
	v_cvt_pk_f32_fp8_sdwa v[136:137], v137 src0_sel:WORD_1
	v_lshlrev_b32_e32 v138, 16, v139
	v_and_b32_e32 v139, 0xffff0000, v139
	v_pk_fma_f32 v[134:135], v[210:211], v[202:203], v[134:135]
	v_lshlrev_b32_e32 v142, 16, v140
	v_and_b32_e32 v143, 0xffff0000, v140
	v_pk_fma_f32 v[134:135], v[212:213], v[138:139], v[134:135]
	v_lshlrev_b32_e32 v140, 16, v141
	v_and_b32_e32 v141, 0xffff0000, v141
	v_pk_fma_f32 v[134:135], v[214:215], v[142:143], v[134:135]
	v_cvt_pk_f32_fp8_e32 v[210:211], v131
	v_pk_fma_f32 v[134:135], v[136:137], v[140:141], v[134:135]
	v_cvt_pk_f32_fp8_sdwa v[136:137], v130 src0_sel:WORD_1
	v_add_f32_e32 v167, v134, v135
	v_cvt_pk_f32_fp8_e32 v[134:135], v130
	v_cvt_pk_f32_fp8_sdwa v[130:131], v131 src0_sel:WORD_1
	v_pk_fma_f32 v[134:135], v[134:135], v[204:205], 0 op_sel_hi:[1,1,0]
	s_nop 0
	v_pk_fma_f32 v[134:135], v[136:137], v[206:207], v[134:135]
	v_cvt_pk_f32_fp8_sdwa v[136:137], v132 src0_sel:WORD_1
	v_pk_fma_f32 v[134:135], v[210:211], v[208:209], v[134:135]
	v_cvt_pk_f32_fp8_e32 v[210:211], v133
	v_pk_fma_f32 v[130:131], v[130:131], v[144:145], v[134:135]
	v_cvt_pk_f32_fp8_e32 v[134:135], v132
	v_cvt_pk_f32_fp8_sdwa v[132:133], v133 src0_sel:WORD_1
	v_pk_fma_f32 v[130:131], v[134:135], v[202:203], v[130:131]
	s_nop 0
	v_pk_fma_f32 v[130:131], v[136:137], v[138:139], v[130:131]
	v_cvt_pk_f32_fp8_e32 v[134:135], v127
	v_pk_fma_f32 v[130:131], v[210:211], v[142:143], v[130:131]
	s_nop 0
	v_pk_fma_f32 v[130:131], v[132:133], v[140:141], v[130:131]
	v_cvt_pk_f32_fp8_sdwa v[132:133], v126 src0_sel:WORD_1
	v_add_f32_e32 v136, v130, v131
	v_cvt_pk_f32_fp8_e32 v[130:131], v126
	v_cvt_pk_f32_fp8_sdwa v[126:127], v127 src0_sel:WORD_1
	v_pk_fma_f32 v[130:131], v[130:131], v[204:205], 0 op_sel_hi:[1,1,0]
	s_nop 0
	v_pk_fma_f32 v[130:131], v[132:133], v[206:207], v[130:131]
	v_cvt_pk_f32_fp8_sdwa v[132:133], v128 src0_sel:WORD_1
	v_pk_fma_f32 v[130:131], v[134:135], v[208:209], v[130:131]
	v_cvt_pk_f32_fp8_e32 v[134:135], v129
	v_pk_fma_f32 v[126:127], v[126:127], v[144:145], v[130:131]
	v_cvt_pk_f32_fp8_e32 v[130:131], v128
	v_cvt_pk_f32_fp8_sdwa v[128:129], v129 src0_sel:WORD_1
	v_pk_fma_f32 v[126:127], v[130:131], v[202:203], v[126:127]
	s_nop 0
	v_pk_fma_f32 v[126:127], v[132:133], v[138:139], v[126:127]
	v_cvt_pk_f32_fp8_e32 v[130:131], v123
	v_pk_fma_f32 v[126:127], v[134:135], v[142:143], v[126:127]
	s_nop 0
	v_pk_fma_f32 v[126:127], v[128:129], v[140:141], v[126:127]
	v_cvt_pk_f32_fp8_sdwa v[128:129], v122 src0_sel:WORD_1
	v_add_f32_e32 v132, v126, v127
	v_cvt_pk_f32_fp8_e32 v[126:127], v122
	v_cvt_pk_f32_fp8_sdwa v[122:123], v123 src0_sel:WORD_1
	v_pk_fma_f32 v[126:127], v[126:127], v[204:205], 0 op_sel_hi:[1,1,0]
	s_nop 0
	v_pk_fma_f32 v[126:127], v[128:129], v[206:207], v[126:127]
	v_cvt_pk_f32_fp8_sdwa v[128:129], v124 src0_sel:WORD_1
	v_pk_fma_f32 v[126:127], v[130:131], v[208:209], v[126:127]
	v_cvt_pk_f32_fp8_e32 v[130:131], v125
	v_pk_fma_f32 v[122:123], v[122:123], v[144:145], v[126:127]
	v_cvt_pk_f32_fp8_e32 v[126:127], v124
	v_cvt_pk_f32_fp8_sdwa v[124:125], v125 src0_sel:WORD_1
	v_pk_fma_f32 v[122:123], v[126:127], v[202:203], v[122:123]
	s_nop 0
	v_pk_fma_f32 v[122:123], v[128:129], v[138:139], v[122:123]
	v_cvt_pk_f32_fp8_e32 v[126:127], v119
	v_pk_fma_f32 v[122:123], v[130:131], v[142:143], v[122:123]
	s_nop 0
	v_pk_fma_f32 v[122:123], v[124:125], v[140:141], v[122:123]
	v_cvt_pk_f32_fp8_sdwa v[124:125], v118 src0_sel:WORD_1
	v_add_f32_e32 v128, v122, v123
	v_cvt_pk_f32_fp8_e32 v[122:123], v118
	v_cvt_pk_f32_fp8_sdwa v[118:119], v119 src0_sel:WORD_1
	v_pk_fma_f32 v[122:123], v[122:123], v[204:205], 0 op_sel_hi:[1,1,0]
	s_nop 0
	v_pk_fma_f32 v[122:123], v[124:125], v[206:207], v[122:123]
	v_cvt_pk_f32_fp8_sdwa v[124:125], v120 src0_sel:WORD_1
	v_pk_fma_f32 v[122:123], v[126:127], v[208:209], v[122:123]
	v_cvt_pk_f32_fp8_e32 v[126:127], v121
	v_pk_fma_f32 v[118:119], v[118:119], v[144:145], v[122:123]
	v_cvt_pk_f32_fp8_e32 v[122:123], v120
	v_cvt_pk_f32_fp8_sdwa v[120:121], v121 src0_sel:WORD_1
	v_pk_fma_f32 v[118:119], v[122:123], v[202:203], v[118:119]
	s_nop 0
	v_pk_fma_f32 v[118:119], v[124:125], v[138:139], v[118:119]
	v_cvt_pk_f32_fp8_e32 v[122:123], v115
	v_pk_fma_f32 v[118:119], v[126:127], v[142:143], v[118:119]
	s_nop 0
	v_pk_fma_f32 v[118:119], v[120:121], v[140:141], v[118:119]
	v_cvt_pk_f32_fp8_sdwa v[120:121], v114 src0_sel:WORD_1
	v_add_f32_e32 v124, v118, v119
	v_cvt_pk_f32_fp8_e32 v[118:119], v114
	v_cvt_pk_f32_fp8_sdwa v[114:115], v115 src0_sel:WORD_1
	v_pk_fma_f32 v[118:119], v[118:119], v[204:205], 0 op_sel_hi:[1,1,0]
	s_nop 0
	v_pk_fma_f32 v[118:119], v[120:121], v[206:207], v[118:119]
; DI void dn2_math(const u32x4 (&W)[16], u32x4 x0, u32x4 x1, float* __restrict__ parow, int lane) {
;     ...
;   for (int j = 0; j < 16; ++j) {
;     f2 s2 = {0.f, 0.f};
; #pragma unroll
;     for (int d = 0; d < 4; ++d) {
;       f2 lo = __builtin_amdgcn_cvt_pk_f32_fp8((int)W[j][d], false);
;       f2 hi = __builtin_amdgcn_cvt_pk_f32_fp8((int)W[j][d], true);
;       s2 = lo * xf[2 * d] + s2;
;       s2 = hi * xf[2 * d + 1] + s2;
;     }
;     pv[j] = s2.x + s2.y;
;   }
	v_cvt_pk_f32_fp8_sdwa v[120:121], v116 src0_sel:WORD_1
	v_pk_fma_f32 v[118:119], v[122:123], v[208:209], v[118:119]
	v_cvt_pk_f32_fp8_e32 v[122:123], v117
	v_pk_fma_f32 v[114:115], v[114:115], v[144:145], v[118:119]
	v_cvt_pk_f32_fp8_e32 v[118:119], v116
	v_cvt_pk_f32_fp8_sdwa v[116:117], v117 src0_sel:WORD_1
	v_pk_fma_f32 v[114:115], v[118:119], v[202:203], v[114:115]
	s_nop 0
	v_pk_fma_f32 v[114:115], v[120:121], v[138:139], v[114:115]
	v_cvt_pk_f32_fp8_e32 v[118:119], v111
	v_pk_fma_f32 v[114:115], v[122:123], v[142:143], v[114:115]
	s_nop 0
	v_pk_fma_f32 v[114:115], v[116:117], v[140:141], v[114:115]
	v_cvt_pk_f32_fp8_sdwa v[116:117], v110 src0_sel:WORD_1
	v_add_f32_e32 v120, v114, v115
	v_cvt_pk_f32_fp8_e32 v[114:115], v110
	v_cvt_pk_f32_fp8_sdwa v[110:111], v111 src0_sel:WORD_1
	v_pk_fma_f32 v[114:115], v[114:115], v[204:205], 0 op_sel_hi:[1,1,0]
	s_nop 0
	v_pk_fma_f32 v[114:115], v[116:117], v[206:207], v[114:115]
	v_cvt_pk_f32_fp8_sdwa v[116:117], v112 src0_sel:WORD_1
	v_pk_fma_f32 v[114:115], v[118:119], v[208:209], v[114:115]
	v_cvt_pk_f32_fp8_e32 v[118:119], v113
	v_pk_fma_f32 v[110:111], v[110:111], v[144:145], v[114:115]
	v_cvt_pk_f32_fp8_e32 v[114:115], v112
	v_cvt_pk_f32_fp8_sdwa v[112:113], v113 src0_sel:WORD_1
	v_pk_fma_f32 v[110:111], v[114:115], v[202:203], v[110:111]
	s_nop 0
	v_pk_fma_f32 v[110:111], v[116:117], v[138:139], v[110:111]
	v_cvt_pk_f32_fp8_e32 v[114:115], v107
	v_pk_fma_f32 v[110:111], v[118:119], v[142:143], v[110:111]
	s_nop 0
	v_pk_fma_f32 v[110:111], v[112:113], v[140:141], v[110:111]
	v_cvt_pk_f32_fp8_sdwa v[112:113], v106 src0_sel:WORD_1
	v_add_f32_e32 v116, v110, v111
	v_cvt_pk_f32_fp8_e32 v[110:111], v106
	v_cvt_pk_f32_fp8_sdwa v[106:107], v107 src0_sel:WORD_1
	v_pk_fma_f32 v[110:111], v[110:111], v[204:205], 0 op_sel_hi:[1,1,0]
	s_nop 0
	v_pk_fma_f32 v[110:111], v[112:113], v[206:207], v[110:111]
	v_cvt_pk_f32_fp8_sdwa v[112:113], v108 src0_sel:WORD_1
	v_pk_fma_f32 v[110:111], v[114:115], v[208:209], v[110:111]
	v_cvt_pk_f32_fp8_e32 v[114:115], v109
	v_pk_fma_f32 v[106:107], v[106:107], v[144:145], v[110:111]
	v_cvt_pk_f32_fp8_e32 v[110:111], v108
	v_cvt_pk_f32_fp8_sdwa v[108:109], v109 src0_sel:WORD_1
	v_pk_fma_f32 v[106:107], v[110:111], v[202:203], v[106:107]
	s_nop 0
	v_pk_fma_f32 v[106:107], v[112:113], v[138:139], v[106:107]
	v_cvt_pk_f32_fp8_e32 v[110:111], v103
	v_pk_fma_f32 v[106:107], v[114:115], v[142:143], v[106:107]
	s_nop 0
	v_pk_fma_f32 v[106:107], v[108:109], v[140:141], v[106:107]
	v_cvt_pk_f32_fp8_sdwa v[108:109], v102 src0_sel:WORD_1
	v_add_f32_e32 v112, v106, v107
	v_cvt_pk_f32_fp8_e32 v[106:107], v102
	v_cvt_pk_f32_fp8_sdwa v[102:103], v103 src0_sel:WORD_1
	v_pk_fma_f32 v[106:107], v[106:107], v[204:205], 0 op_sel_hi:[1,1,0]
	s_nop 0
	v_pk_fma_f32 v[106:107], v[108:109], v[206:207], v[106:107]
	v_cvt_pk_f32_fp8_sdwa v[108:109], v104 src0_sel:WORD_1
	v_pk_fma_f32 v[106:107], v[110:111], v[208:209], v[106:107]
	v_cvt_pk_f32_fp8_e32 v[110:111], v105
	v_pk_fma_f32 v[102:103], v[102:103], v[144:145], v[106:107]
	v_cvt_pk_f32_fp8_e32 v[106:107], v104
	v_cvt_pk_f32_fp8_sdwa v[104:105], v105 src0_sel:WORD_1
	v_pk_fma_f32 v[102:103], v[106:107], v[202:203], v[102:103]
	s_nop 0
	v_pk_fma_f32 v[102:103], v[108:109], v[138:139], v[102:103]
	v_cvt_pk_f32_fp8_e32 v[106:107], v99
	v_pk_fma_f32 v[102:103], v[110:111], v[142:143], v[102:103]
	s_nop 0
	v_pk_fma_f32 v[102:103], v[104:105], v[140:141], v[102:103]
	v_cvt_pk_f32_fp8_sdwa v[104:105], v98 src0_sel:WORD_1
	v_add_f32_e32 v108, v102, v103
	v_cvt_pk_f32_fp8_e32 v[102:103], v98
	v_cvt_pk_f32_fp8_sdwa v[98:99], v99 src0_sel:WORD_1
	v_pk_fma_f32 v[102:103], v[102:103], v[204:205], 0 op_sel_hi:[1,1,0]
	s_nop 0
	v_pk_fma_f32 v[102:103], v[104:105], v[206:207], v[102:103]
	v_cvt_pk_f32_fp8_sdwa v[104:105], v100 src0_sel:WORD_1
	v_pk_fma_f32 v[102:103], v[106:107], v[208:209], v[102:103]
	v_cvt_pk_f32_fp8_e32 v[106:107], v101
	v_pk_fma_f32 v[98:99], v[98:99], v[144:145], v[102:103]
	v_cvt_pk_f32_fp8_e32 v[102:103], v100
	v_cvt_pk_f32_fp8_sdwa v[100:101], v101 src0_sel:WORD_1
	v_pk_fma_f32 v[98:99], v[102:103], v[202:203], v[98:99]
	s_nop 0
	v_pk_fma_f32 v[98:99], v[104:105], v[138:139], v[98:99]
	v_cvt_pk_f32_fp8_e32 v[102:103], v95
	v_pk_fma_f32 v[98:99], v[106:107], v[142:143], v[98:99]
	s_nop 0
	v_pk_fma_f32 v[98:99], v[100:101], v[140:141], v[98:99]
	v_cvt_pk_f32_fp8_sdwa v[100:101], v94 src0_sel:WORD_1
	v_add_f32_e32 v104, v98, v99
	v_cvt_pk_f32_fp8_e32 v[98:99], v94
	v_cvt_pk_f32_fp8_sdwa v[94:95], v95 src0_sel:WORD_1
	v_pk_fma_f32 v[98:99], v[98:99], v[204:205], 0 op_sel_hi:[1,1,0]
	s_nop 0
	v_pk_fma_f32 v[98:99], v[100:101], v[206:207], v[98:99]
	v_cvt_pk_f32_fp8_sdwa v[100:101], v96 src0_sel:WORD_1
	v_pk_fma_f32 v[98:99], v[102:103], v[208:209], v[98:99]
	v_cvt_pk_f32_fp8_e32 v[102:103], v97
	v_pk_fma_f32 v[94:95], v[94:95], v[144:145], v[98:99]
	v_cvt_pk_f32_fp8_e32 v[98:99], v96
	v_cvt_pk_f32_fp8_sdwa v[96:97], v97 src0_sel:WORD_1
	v_pk_fma_f32 v[94:95], v[98:99], v[202:203], v[94:95]
	s_nop 0
	v_pk_fma_f32 v[94:95], v[100:101], v[138:139], v[94:95]
	v_cvt_pk_f32_fp8_e32 v[98:99], v91
	v_pk_fma_f32 v[94:95], v[102:103], v[142:143], v[94:95]
	s_nop 0
	v_pk_fma_f32 v[94:95], v[96:97], v[140:141], v[94:95]
	v_cvt_pk_f32_fp8_sdwa v[96:97], v90 src0_sel:WORD_1
	v_add_f32_e32 v100, v94, v95
	v_cvt_pk_f32_fp8_e32 v[94:95], v90
	v_cvt_pk_f32_fp8_sdwa v[90:91], v91 src0_sel:WORD_1
	v_pk_fma_f32 v[94:95], v[94:95], v[204:205], 0 op_sel_hi:[1,1,0]
	s_nop 0
	v_pk_fma_f32 v[94:95], v[96:97], v[206:207], v[94:95]
	v_cvt_pk_f32_fp8_sdwa v[96:97], v92 src0_sel:WORD_1
	v_pk_fma_f32 v[94:95], v[98:99], v[208:209], v[94:95]
	v_cvt_pk_f32_fp8_e32 v[98:99], v93
; DI void dn2_math(const u32x4 (&W)[16], u32x4 x0, u32x4 x1, float* __restrict__ parow, int lane) {
;     ...
;   for (int j = 0; j < 16; ++j) {
;     f2 s2 = {0.f, 0.f};
; #pragma unroll
;     for (int d = 0; d < 4; ++d) {
;       f2 lo = __builtin_amdgcn_cvt_pk_f32_fp8((int)W[j][d], false);
;       f2 hi = __builtin_amdgcn_cvt_pk_f32_fp8((int)W[j][d], true);
;       s2 = lo * xf[2 * d] + s2;
;       s2 = hi * xf[2 * d + 1] + s2;
;     }
;     pv[j] = s2.x + s2.y;
;   }
;   const bool b2 = lane & 4, b1 = lane & 2, b0 = lane & 1;
;   float q8[8];
; #pragma unroll
;   for (int i = 0; i < 8; ++i) { float snd = b2 ? pv[i] : pv[i + 8]; float kp = b2 ? pv[i + 8] : pv[i]; q8[i] = kp + __shfl_xor(snd, 4); }
;   float q4[4];
; #pragma unroll
;   for (int i = 0; i < 4; ++i) { float snd = b1 ? q8[i] : q8[i + 4]; float kp = b1 ? q8[i + 4] : q8[i]; q4[i] = kp + __shfl_xor(snd, 2); }
;   float r2[2];
; #pragma unroll
;   for (int i = 0; i < 2; ++i) { float snd = b0 ? q4[i] : q4[i + 2]; float kp = b0 ? q4[i + 2] : q4[i]; r2[i] = kp + __shfl_xor(snd, 1); }
;   const int j0 = (b0 ? 2 : 0) + (b1 ? 4 : 0) + (b2 ? 8 : 0);
;   const int grp = lane >> 3;
;   parow[8 * j0 + grp] = r2[0];
;   parow[8 * (j0 + 1) + grp] = r2[1];
	v_pk_fma_f32 v[90:91], v[90:91], v[144:145], v[94:95]
	v_cvt_pk_f32_fp8_e32 v[94:95], v92
	v_cvt_pk_f32_fp8_sdwa v[92:93], v93 src0_sel:WORD_1
	v_pk_fma_f32 v[90:91], v[94:95], v[202:203], v[90:91]
	s_nop 0
	v_pk_fma_f32 v[90:91], v[96:97], v[138:139], v[90:91]
	v_cvt_pk_f32_fp8_e32 v[94:95], v87
	v_pk_fma_f32 v[90:91], v[98:99], v[142:143], v[90:91]
	s_nop 0
	v_pk_fma_f32 v[90:91], v[92:93], v[140:141], v[90:91]
	v_cvt_pk_f32_fp8_sdwa v[92:93], v86 src0_sel:WORD_1
	v_add_f32_e32 v96, v90, v91
	v_cvt_pk_f32_fp8_e32 v[90:91], v86
	v_cvt_pk_f32_fp8_sdwa v[86:87], v87 src0_sel:WORD_1
	v_pk_fma_f32 v[90:91], v[90:91], v[204:205], 0 op_sel_hi:[1,1,0]
	s_nop 0
	v_pk_fma_f32 v[90:91], v[92:93], v[206:207], v[90:91]
	v_cvt_pk_f32_fp8_sdwa v[92:93], v88 src0_sel:WORD_1
	v_pk_fma_f32 v[90:91], v[94:95], v[208:209], v[90:91]
	v_cvt_pk_f32_fp8_e32 v[94:95], v89
	v_pk_fma_f32 v[86:87], v[86:87], v[144:145], v[90:91]
	v_cvt_pk_f32_fp8_e32 v[90:91], v88
	v_cvt_pk_f32_fp8_sdwa v[88:89], v89 src0_sel:WORD_1
	v_pk_fma_f32 v[86:87], v[90:91], v[202:203], v[86:87]
	s_nop 0
	v_pk_fma_f32 v[86:87], v[92:93], v[138:139], v[86:87]
	v_cvt_pk_f32_fp8_e32 v[90:91], v83
	v_pk_fma_f32 v[86:87], v[94:95], v[142:143], v[86:87]
	s_nop 0
	v_pk_fma_f32 v[86:87], v[88:89], v[140:141], v[86:87]
	v_cvt_pk_f32_fp8_sdwa v[88:89], v82 src0_sel:WORD_1
	v_add_f32_e32 v92, v86, v87
	v_cvt_pk_f32_fp8_e32 v[86:87], v82
	v_cvt_pk_f32_fp8_sdwa v[82:83], v83 src0_sel:WORD_1
	v_pk_fma_f32 v[86:87], v[86:87], v[204:205], 0 op_sel_hi:[1,1,0]
	s_nop 0
	v_pk_fma_f32 v[86:87], v[88:89], v[206:207], v[86:87]
	v_cvt_pk_f32_fp8_sdwa v[88:89], v84 src0_sel:WORD_1
	v_pk_fma_f32 v[86:87], v[90:91], v[208:209], v[86:87]
	v_cvt_pk_f32_fp8_e32 v[90:91], v85
	v_pk_fma_f32 v[82:83], v[82:83], v[144:145], v[86:87]
	v_cvt_pk_f32_fp8_e32 v[86:87], v84
	v_cvt_pk_f32_fp8_sdwa v[84:85], v85 src0_sel:WORD_1
	v_pk_fma_f32 v[82:83], v[86:87], v[202:203], v[82:83]
	s_nop 0
	v_pk_fma_f32 v[82:83], v[88:89], v[138:139], v[82:83]
	v_cvt_pk_f32_fp8_e32 v[86:87], v79
	v_pk_fma_f32 v[82:83], v[90:91], v[142:143], v[82:83]
	s_nop 0
	v_pk_fma_f32 v[82:83], v[84:85], v[140:141], v[82:83]
	v_cvt_pk_f32_fp8_sdwa v[84:85], v78 src0_sel:WORD_1
	v_add_f32_e32 v88, v82, v83
	v_cvt_pk_f32_fp8_e32 v[82:83], v78
	v_cvt_pk_f32_fp8_sdwa v[78:79], v79 src0_sel:WORD_1
	v_pk_fma_f32 v[82:83], v[82:83], v[204:205], 0 op_sel_hi:[1,1,0]
	s_nop 0
	v_pk_fma_f32 v[82:83], v[84:85], v[206:207], v[82:83]
	v_cvt_pk_f32_fp8_sdwa v[84:85], v80 src0_sel:WORD_1
	v_pk_fma_f32 v[82:83], v[86:87], v[208:209], v[82:83]
	v_cvt_pk_f32_fp8_e32 v[86:87], v81
	v_pk_fma_f32 v[78:79], v[78:79], v[144:145], v[82:83]
	v_cvt_pk_f32_fp8_e32 v[82:83], v80
	v_cvt_pk_f32_fp8_sdwa v[80:81], v81 src0_sel:WORD_1
	v_pk_fma_f32 v[78:79], v[82:83], v[202:203], v[78:79]
	s_nop 0
	v_pk_fma_f32 v[78:79], v[84:85], v[138:139], v[78:79]
	v_cvt_pk_f32_fp8_e32 v[82:83], v75
	v_pk_fma_f32 v[78:79], v[86:87], v[142:143], v[78:79]
	s_nop 0
	v_pk_fma_f32 v[78:79], v[80:81], v[140:141], v[78:79]
	v_cvt_pk_f32_fp8_sdwa v[80:81], v74 src0_sel:WORD_1
	v_add_f32_e32 v84, v78, v79
	v_cvt_pk_f32_fp8_e32 v[78:79], v74
	v_cvt_pk_f32_fp8_sdwa v[74:75], v75 src0_sel:WORD_1
	v_pk_fma_f32 v[78:79], v[78:79], v[204:205], 0 op_sel_hi:[1,1,0]
	s_nop 0
	v_pk_fma_f32 v[78:79], v[80:81], v[206:207], v[78:79]
	v_cvt_pk_f32_fp8_sdwa v[80:81], v76 src0_sel:WORD_1
	v_pk_fma_f32 v[78:79], v[82:83], v[208:209], v[78:79]
	v_cvt_pk_f32_fp8_e32 v[82:83], v77
	v_pk_fma_f32 v[74:75], v[74:75], v[144:145], v[78:79]
	v_cvt_pk_f32_fp8_e32 v[78:79], v76
	v_cvt_pk_f32_fp8_sdwa v[76:77], v77 src0_sel:WORD_1
	v_pk_fma_f32 v[74:75], v[78:79], v[202:203], v[74:75]
	s_nop 0
	v_pk_fma_f32 v[74:75], v[80:81], v[138:139], v[74:75]
	v_pk_fma_f32 v[74:75], v[82:83], v[142:143], v[74:75]
	v_pk_fma_f32 v[74:75], v[76:77], v[140:141], v[74:75]
	v_add_f32_e32 v74, v74, v75
	s_nop 1
	v_add_f32_dpp v75, v167, v167 row_shl:4 row_mask:0xf bank_mask:0x5
	v_add_f32_dpp v75, v108, v108 row_shr:4 row_mask:0xf bank_mask:0xa
	v_add_f32_dpp v76, v136, v136 row_shl:4 row_mask:0xf bank_mask:0x5
	v_add_f32_dpp v76, v104, v104 row_shr:4 row_mask:0xf bank_mask:0xa
	v_add_f32_dpp v77, v132, v132 row_shl:4 row_mask:0xf bank_mask:0x5
	v_add_f32_dpp v77, v100, v100 row_shr:4 row_mask:0xf bank_mask:0xa
	v_add_f32_dpp v78, v128, v128 row_shl:4 row_mask:0xf bank_mask:0x5
	v_add_f32_dpp v78, v96, v96 row_shr:4 row_mask:0xf bank_mask:0xa
	v_add_f32_dpp v79, v124, v124 row_shl:4 row_mask:0xf bank_mask:0x5
	v_add_f32_dpp v79, v92, v92 row_shr:4 row_mask:0xf bank_mask:0xa
	v_add_f32_dpp v80, v120, v120 row_shl:4 row_mask:0xf bank_mask:0x5
	v_add_f32_dpp v80, v88, v88 row_shr:4 row_mask:0xf bank_mask:0xa
	v_add_f32_dpp v81, v116, v116 row_shl:4 row_mask:0xf bank_mask:0x5
	v_add_f32_dpp v81, v84, v84 row_shr:4 row_mask:0xf bank_mask:0xa
	v_add_f32_dpp v74, v74, v74 row_shr:4 row_mask:0xf bank_mask:0xa
	v_add_f32_dpp v74, v112, v112 row_shl:4 row_mask:0xf bank_mask:0x5
	s_nop 1
	v_add_f32_dpp v75, v75, v75 quad_perm:[2,3,0,1] row_mask:0xf bank_mask:0xf
	v_add_f32_dpp v79, v79, v79 quad_perm:[2,3,0,1] row_mask:0xf bank_mask:0xf
	v_cndmask_b32_e64 v75, v79, v75, s[10:11]
	v_add_f32_dpp v77, v77, v77 quad_perm:[2,3,0,1] row_mask:0xf bank_mask:0xf
	v_add_f32_dpp v81, v81, v81 quad_perm:[2,3,0,1] row_mask:0xf bank_mask:0xf
	v_cndmask_b32_e64 v77, v81, v77, s[10:11]
	v_add_f32_dpp v76, v76, v76 quad_perm:[2,3,0,1] row_mask:0xf bank_mask:0xf
	v_add_f32_dpp v80, v80, v80 quad_perm:[2,3,0,1] row_mask:0xf bank_mask:0xf
	v_cndmask_b32_e64 v76, v80, v76, s[10:11]
	v_add_f32_dpp v78, v78, v78 quad_perm:[2,3,0,1] row_mask:0xf bank_mask:0xf
	v_add_f32_dpp v74, v74, v74 quad_perm:[2,3,0,1] row_mask:0xf bank_mask:0xf
	v_cndmask_b32_e64 v74, v74, v78, s[10:11]
	s_nop 1
	v_add_f32_dpp v75, v75, v75 quad_perm:[1,0,3,2] row_mask:0xf bank_mask:0xf
	v_add_f32_dpp v77, v77, v77 quad_perm:[1,0,3,2] row_mask:0xf bank_mask:0xf
	v_cndmask_b32_e64 v75, v77, v75, s[12:13]
	v_add_f32_dpp v76, v76, v76 quad_perm:[1,0,3,2] row_mask:0xf bank_mask:0xf
	v_add_f32_dpp v74, v74, v74 quad_perm:[1,0,3,2] row_mask:0xf bank_mask:0xf
	v_cndmask_b32_e64 v74, v74, v76, s[12:13]
	global_store_dword v[200:201], v75, off
	global_store_dword v[200:201], v74, off offset:32
	v_lshl_add_u64 v[198:199], v[198:199], 0, s[20:21]
	v_add_u32_e32 v165, 0x400, v165
	v_lshl_add_u64 v[200:201], v[200:201], 0, s[36:37]
	s_and_b64 vcc, exec, s[28:29]
	s_cbranch_vccnz .LBB0_1504
; DI float bflo(u32 u) { return __uint_as_float(u << 16); }
; DI float bfhi(u32 u) { return __uint_as_float(u & 0xffff0000u); }
; DI void dn2_issue(u32x4 (&W)[16], const int* pl, const unsigned char* wbase, int grp) {
; #pragma unroll
;   for (int j = 0; j < 16; ++j) W[j] = *(const u32x4*)(wbase + (size_t)pl[8 * j + grp] * 1024);
; }
; DI void dn2_math(const u32x4 (&W)[16], u32x4 x0, u32x4 x1, float* __restrict__ parow, int lane) {
;   f2 xf[8];
; #pragma unroll
;   for (int q = 0; q < 4; ++q) { xf[q] = f2{bflo(x0[q]), bfhi(x0[q])}; xf[4 + q] = f2{bflo(x1[q]), bfhi(x1[q])}; }
;   float pv[16];
; #pragma unroll
;   for (int j = 0; j < 16; ++j) {
;     f2 s2 = {0.f, 0.f};
; #pragma unroll
;     for (int d = 0; d < 4; ++d) {
;       f2 lo = __builtin_amdgcn_cvt_pk_f32_fp8((int)W[j][d], false);
;       f2 hi = __builtin_amdgcn_cvt_pk_f32_fp8((int)W[j][d], true);
;       s2 = lo * xf[2 * d] + s2;
;       s2 = hi * xf[2 * d + 1] + s2;
;     }
;     pv[j] = s2.x + s2.y;
;   }
.LBB0_1517:
	ds_read2_b32 v[134:135], v165 offset1:8
	ds_read2_b32 v[126:127], v165 offset0:16 offset1:24
	ds_read2_b32 v[118:119], v165 offset0:32 offset1:40
	ds_read2_b32 v[110:111], v165 offset0:48 offset1:56
	ds_read2_b32 v[102:103], v165 offset0:64 offset1:72
	ds_read2_b32 v[94:95], v165 offset0:80 offset1:88
	ds_read2_b32 v[86:87], v165 offset0:96 offset1:104
	ds_read2_b32 v[78:79], v165 offset0:112 offset1:120
	s_waitcnt lgkmcnt(7)
	v_lshl_add_u32 v130, v135, 10, v250
	v_lshl_add_u32 v134, v134, 10, v250
	global_load_dwordx4 v[134:137], v134, s[98:99]
	global_load_dwordx4 v[130:133], v130, s[98:99]
	s_waitcnt lgkmcnt(6)
	v_lshl_add_u32 v122, v127, 10, v250
	v_lshl_add_u32 v126, v126, 10, v250
	global_load_dwordx4 v[126:129], v126, s[98:99]
	global_load_dwordx4 v[122:125], v122, s[98:99]
	s_waitcnt lgkmcnt(5)
	v_lshl_add_u32 v114, v119, 10, v250
	v_lshl_add_u32 v118, v118, 10, v250
	global_load_dwordx4 v[118:121], v118, s[98:99]
	global_load_dwordx4 v[114:117], v114, s[98:99]
	s_waitcnt lgkmcnt(4)
	v_lshl_add_u32 v106, v111, 10, v250
	v_lshl_add_u32 v110, v110, 10, v250
	global_load_dwordx4 v[110:113], v110, s[98:99]
	global_load_dwordx4 v[106:109], v106, s[98:99]
	s_waitcnt lgkmcnt(3)
	v_lshl_add_u32 v98, v103, 10, v250
	v_lshl_add_u32 v102, v102, 10, v250
	global_load_dwordx4 v[102:105], v102, s[98:99]
	global_load_dwordx4 v[98:101], v98, s[98:99]
	s_waitcnt lgkmcnt(2)
	v_lshl_add_u32 v90, v95, 10, v250
	v_lshl_add_u32 v94, v94, 10, v250
	global_load_dwordx4 v[94:97], v94, s[98:99]
	global_load_dwordx4 v[90:93], v90, s[98:99]
	s_waitcnt lgkmcnt(1)
	v_lshl_add_u32 v82, v87, 10, v250
	v_lshl_add_u32 v86, v86, 10, v250
	global_load_dwordx4 v[86:89], v86, s[98:99]
	global_load_dwordx4 v[82:85], v82, s[98:99]
	s_waitcnt lgkmcnt(0)
	v_lshl_add_u32 v74, v79, 10, v250
	v_lshl_add_u32 v78, v78, 10, v250
	global_load_dwordx4 v[78:81], v78, s[98:99]
	global_load_dwordx4 v[74:77], v74, s[98:99]
	s_nop 0
	global_load_dwordx4 v[138:141], v[198:199], off offset:-2032
	global_load_dwordx4 v[142:145], v[198:199], off offset:-2048
	s_waitcnt vmcnt(35)
	v_cvt_pk_f32_fp8_e32 v[230:231], v2
	v_cvt_pk_f32_fp8_sdwa v[232:233], v2 src0_sel:WORD_1
	v_cvt_pk_f32_fp8_e32 v[234:235], v3
	s_waitcnt vmcnt(18)
	v_lshlrev_b32_e32 v210, 16, v70
	v_and_b32_e32 v211, 0xffff0000, v70
	v_cvt_pk_f32_fp8_sdwa v[236:237], v3 src0_sel:WORD_1
	v_lshlrev_b32_e32 v212, 16, v71
	v_and_b32_e32 v213, 0xffff0000, v71
	v_pk_fma_f32 v[230:231], v[230:231], v[210:211], 0 op_sel_hi:[1,1,0]
	v_lshlrev_b32_e32 v214, 16, v72
	v_and_b32_e32 v215, 0xffff0000, v72
	v_pk_fma_f32 v[230:231], v[232:233], v[212:213], v[230:231]
	v_cvt_pk_f32_fp8_e32 v[232:233], v4
	v_lshlrev_b32_e32 v216, 16, v73
	v_and_b32_e32 v217, 0xffff0000, v73
	v_pk_fma_f32 v[230:231], v[234:235], v[214:215], v[230:231]
	v_cvt_pk_f32_fp8_sdwa v[234:235], v4 src0_sel:WORD_1
	v_pk_fma_f32 v[230:231], v[236:237], v[216:217], v[230:231]
	v_cvt_pk_f32_fp8_e32 v[236:237], v5
	v_lshlrev_b32_e32 v202, 16, v66
	v_and_b32_e32 v203, 0xffff0000, v66
	v_cvt_pk_f32_fp8_sdwa v[238:239], v5 src0_sel:WORD_1
	v_lshlrev_b32_e32 v204, 16, v67
	v_and_b32_e32 v205, 0xffff0000, v67
	v_pk_fma_f32 v[230:231], v[232:233], v[202:203], v[230:231]
	v_lshlrev_b32_e32 v206, 16, v68
	v_and_b32_e32 v207, 0xffff0000, v68
	v_pk_fma_f32 v[230:231], v[234:235], v[204:205], v[230:231]
	v_lshlrev_b32_e32 v208, 16, v69
	v_and_b32_e32 v209, 0xffff0000, v69
	v_pk_fma_f32 v[230:231], v[236:237], v[206:207], v[230:231]
	v_cvt_pk_f32_fp8_sdwa v[232:233], v6 src0_sel:WORD_1
	v_pk_fma_f32 v[230:231], v[238:239], v[208:209], v[230:231]
	v_cvt_pk_f32_fp8_e32 v[234:235], v7
	v_add_f32_e32 v167, v230, v231
	v_cvt_pk_f32_fp8_e32 v[230:231], v6
	v_cvt_pk_f32_fp8_sdwa v[236:237], v7 src0_sel:WORD_1
	v_cvt_pk_f32_fp8_sdwa v[238:239], v9 src0_sel:WORD_1
	v_pk_fma_f32 v[230:231], v[230:231], v[210:211], 0 op_sel_hi:[1,1,0]
	s_nop 0
	v_pk_fma_f32 v[230:231], v[232:233], v[212:213], v[230:231]
	v_cvt_pk_f32_fp8_e32 v[232:233], v8
	v_pk_fma_f32 v[230:231], v[234:235], v[214:215], v[230:231]
	v_cvt_pk_f32_fp8_sdwa v[234:235], v8 src0_sel:WORD_1
	v_pk_fma_f32 v[230:231], v[236:237], v[216:217], v[230:231]
	v_cvt_pk_f32_fp8_e32 v[236:237], v9
	v_pk_fma_f32 v[230:231], v[232:233], v[202:203], v[230:231]
	v_cvt_pk_f32_fp8_sdwa v[232:233], v10 src0_sel:WORD_1
	v_pk_fma_f32 v[230:231], v[234:235], v[204:205], v[230:231]
	v_cvt_pk_f32_fp8_e32 v[234:235], v11
	v_pk_fma_f32 v[230:231], v[236:237], v[206:207], v[230:231]
	v_cvt_pk_f32_fp8_sdwa v[236:237], v11 src0_sel:WORD_1
	v_pk_fma_f32 v[230:231], v[238:239], v[208:209], v[230:231]
	v_cvt_pk_f32_fp8_sdwa v[238:239], v13 src0_sel:WORD_1
	v_add_f32_e32 v169, v230, v231
	v_cvt_pk_f32_fp8_e32 v[230:231], v10
	v_pk_fma_f32 v[230:231], v[230:231], v[210:211], 0 op_sel_hi:[1,1,0]
	s_nop 0
	v_pk_fma_f32 v[230:231], v[232:233], v[212:213], v[230:231]
	v_cvt_pk_f32_fp8_e32 v[232:233], v12
	v_pk_fma_f32 v[230:231], v[234:235], v[214:215], v[230:231]
	v_cvt_pk_f32_fp8_sdwa v[234:235], v12 src0_sel:WORD_1
	v_pk_fma_f32 v[230:231], v[236:237], v[216:217], v[230:231]
	v_cvt_pk_f32_fp8_e32 v[236:237], v13
	v_pk_fma_f32 v[230:231], v[232:233], v[202:203], v[230:231]
	v_cvt_pk_f32_fp8_sdwa v[232:233], v14 src0_sel:WORD_1
	v_pk_fma_f32 v[230:231], v[234:235], v[204:205], v[230:231]
	v_cvt_pk_f32_fp8_e32 v[234:235], v15
	v_pk_fma_f32 v[230:231], v[236:237], v[206:207], v[230:231]
	v_cvt_pk_f32_fp8_sdwa v[236:237], v15 src0_sel:WORD_1
	v_pk_fma_f32 v[230:231], v[238:239], v[208:209], v[230:231]
	v_cvt_pk_f32_fp8_sdwa v[238:239], v17 src0_sel:WORD_1
	v_add_f32_e32 v171, v230, v231
	v_cvt_pk_f32_fp8_e32 v[230:231], v14
; DI void dn2_math(const u32x4 (&W)[16], u32x4 x0, u32x4 x1, float* __restrict__ parow, int lane) {
;     ...
;   for (int j = 0; j < 16; ++j) {
;     f2 s2 = {0.f, 0.f};
; #pragma unroll
;     for (int d = 0; d < 4; ++d) {
;       f2 lo = __builtin_amdgcn_cvt_pk_f32_fp8((int)W[j][d], false);
;       f2 hi = __builtin_amdgcn_cvt_pk_f32_fp8((int)W[j][d], true);
;       s2 = lo * xf[2 * d] + s2;
;       s2 = hi * xf[2 * d + 1] + s2;
;     }
;     pv[j] = s2.x + s2.y;
;   }
	v_pk_fma_f32 v[230:231], v[230:231], v[210:211], 0 op_sel_hi:[1,1,0]
	s_nop 0
	v_pk_fma_f32 v[230:231], v[232:233], v[212:213], v[230:231]
	v_cvt_pk_f32_fp8_e32 v[232:233], v16
	v_pk_fma_f32 v[230:231], v[234:235], v[214:215], v[230:231]
	v_cvt_pk_f32_fp8_sdwa v[234:235], v16 src0_sel:WORD_1
	v_pk_fma_f32 v[230:231], v[236:237], v[216:217], v[230:231]
	v_cvt_pk_f32_fp8_e32 v[236:237], v17
	v_pk_fma_f32 v[230:231], v[232:233], v[202:203], v[230:231]
	v_cvt_pk_f32_fp8_sdwa v[232:233], v18 src0_sel:WORD_1
	v_pk_fma_f32 v[230:231], v[234:235], v[204:205], v[230:231]
	v_cvt_pk_f32_fp8_e32 v[234:235], v19
	v_pk_fma_f32 v[230:231], v[236:237], v[206:207], v[230:231]
	v_cvt_pk_f32_fp8_sdwa v[236:237], v19 src0_sel:WORD_1
	v_pk_fma_f32 v[230:231], v[238:239], v[208:209], v[230:231]
	v_cvt_pk_f32_fp8_sdwa v[238:239], v21 src0_sel:WORD_1
	v_add_f32_e32 v173, v230, v231
	v_cvt_pk_f32_fp8_e32 v[230:231], v18
	v_pk_fma_f32 v[230:231], v[230:231], v[210:211], 0 op_sel_hi:[1,1,0]
	s_nop 0
	v_pk_fma_f32 v[230:231], v[232:233], v[212:213], v[230:231]
	v_cvt_pk_f32_fp8_e32 v[232:233], v20
	v_pk_fma_f32 v[230:231], v[234:235], v[214:215], v[230:231]
	v_cvt_pk_f32_fp8_sdwa v[234:235], v20 src0_sel:WORD_1
	v_pk_fma_f32 v[230:231], v[236:237], v[216:217], v[230:231]
	v_cvt_pk_f32_fp8_e32 v[236:237], v21
	v_pk_fma_f32 v[230:231], v[232:233], v[202:203], v[230:231]
	v_cvt_pk_f32_fp8_sdwa v[232:233], v22 src0_sel:WORD_1
	v_pk_fma_f32 v[230:231], v[234:235], v[204:205], v[230:231]
	v_cvt_pk_f32_fp8_e32 v[234:235], v23
	v_pk_fma_f32 v[230:231], v[236:237], v[206:207], v[230:231]
	v_cvt_pk_f32_fp8_sdwa v[236:237], v23 src0_sel:WORD_1
	v_pk_fma_f32 v[230:231], v[238:239], v[208:209], v[230:231]
	v_cvt_pk_f32_fp8_sdwa v[238:239], v25 src0_sel:WORD_1
	v_add_f32_e32 v175, v230, v231
	v_cvt_pk_f32_fp8_e32 v[230:231], v22
	v_pk_fma_f32 v[230:231], v[230:231], v[210:211], 0 op_sel_hi:[1,1,0]
	s_nop 0
	v_pk_fma_f32 v[230:231], v[232:233], v[212:213], v[230:231]
	v_cvt_pk_f32_fp8_e32 v[232:233], v24
	v_pk_fma_f32 v[230:231], v[234:235], v[214:215], v[230:231]
	v_cvt_pk_f32_fp8_sdwa v[234:235], v24 src0_sel:WORD_1
	v_pk_fma_f32 v[230:231], v[236:237], v[216:217], v[230:231]
	v_cvt_pk_f32_fp8_e32 v[236:237], v25
	v_pk_fma_f32 v[230:231], v[232:233], v[202:203], v[230:231]
	v_cvt_pk_f32_fp8_sdwa v[232:233], v26 src0_sel:WORD_1
	v_pk_fma_f32 v[230:231], v[234:235], v[204:205], v[230:231]
	v_cvt_pk_f32_fp8_e32 v[234:235], v27
	v_pk_fma_f32 v[230:231], v[236:237], v[206:207], v[230:231]
	v_cvt_pk_f32_fp8_sdwa v[236:237], v27 src0_sel:WORD_1
	v_pk_fma_f32 v[230:231], v[238:239], v[208:209], v[230:231]
	v_cvt_pk_f32_fp8_sdwa v[238:239], v29 src0_sel:WORD_1
	v_add_f32_e32 v177, v230, v231
	v_cvt_pk_f32_fp8_e32 v[230:231], v26
	v_pk_fma_f32 v[230:231], v[230:231], v[210:211], 0 op_sel_hi:[1,1,0]
	s_nop 0
	v_pk_fma_f32 v[230:231], v[232:233], v[212:213], v[230:231]
	v_cvt_pk_f32_fp8_e32 v[232:233], v28
	v_pk_fma_f32 v[230:231], v[234:235], v[214:215], v[230:231]
	v_cvt_pk_f32_fp8_sdwa v[234:235], v28 src0_sel:WORD_1
	v_pk_fma_f32 v[230:231], v[236:237], v[216:217], v[230:231]
	v_cvt_pk_f32_fp8_e32 v[236:237], v29
	v_pk_fma_f32 v[230:231], v[232:233], v[202:203], v[230:231]
	v_cvt_pk_f32_fp8_sdwa v[232:233], v30 src0_sel:WORD_1
	v_pk_fma_f32 v[230:231], v[234:235], v[204:205], v[230:231]
	v_cvt_pk_f32_fp8_e32 v[234:235], v31
	v_pk_fma_f32 v[230:231], v[236:237], v[206:207], v[230:231]
	v_cvt_pk_f32_fp8_sdwa v[236:237], v31 src0_sel:WORD_1
	v_pk_fma_f32 v[230:231], v[238:239], v[208:209], v[230:231]
	v_cvt_pk_f32_fp8_sdwa v[238:239], v33 src0_sel:WORD_1
	v_add_f32_e32 v179, v230, v231
	v_cvt_pk_f32_fp8_e32 v[230:231], v30
	v_pk_fma_f32 v[230:231], v[230:231], v[210:211], 0 op_sel_hi:[1,1,0]
	s_nop 0
	v_pk_fma_f32 v[230:231], v[232:233], v[212:213], v[230:231]
	v_cvt_pk_f32_fp8_e32 v[232:233], v32
	v_pk_fma_f32 v[230:231], v[234:235], v[214:215], v[230:231]
	v_cvt_pk_f32_fp8_sdwa v[234:235], v32 src0_sel:WORD_1
	v_pk_fma_f32 v[230:231], v[236:237], v[216:217], v[230:231]
	v_cvt_pk_f32_fp8_e32 v[236:237], v33
	v_pk_fma_f32 v[230:231], v[232:233], v[202:203], v[230:231]
	v_cvt_pk_f32_fp8_sdwa v[232:233], v34 src0_sel:WORD_1
	v_pk_fma_f32 v[230:231], v[234:235], v[204:205], v[230:231]
	v_cvt_pk_f32_fp8_e32 v[234:235], v35
	v_pk_fma_f32 v[230:231], v[236:237], v[206:207], v[230:231]
	v_cvt_pk_f32_fp8_sdwa v[236:237], v35 src0_sel:WORD_1
	v_pk_fma_f32 v[230:231], v[238:239], v[208:209], v[230:231]
	v_cvt_pk_f32_fp8_sdwa v[238:239], v37 src0_sel:WORD_1
	v_add_f32_e32 v181, v230, v231
	v_cvt_pk_f32_fp8_e32 v[230:231], v34
	v_pk_fma_f32 v[230:231], v[230:231], v[210:211], 0 op_sel_hi:[1,1,0]
	s_nop 0
	v_pk_fma_f32 v[230:231], v[232:233], v[212:213], v[230:231]
	v_cvt_pk_f32_fp8_e32 v[232:233], v36
	v_pk_fma_f32 v[230:231], v[234:235], v[214:215], v[230:231]
	v_cvt_pk_f32_fp8_sdwa v[234:235], v36 src0_sel:WORD_1
	v_pk_fma_f32 v[230:231], v[236:237], v[216:217], v[230:231]
	v_cvt_pk_f32_fp8_e32 v[236:237], v37
	v_pk_fma_f32 v[230:231], v[232:233], v[202:203], v[230:231]
	v_cvt_pk_f32_fp8_sdwa v[232:233], v38 src0_sel:WORD_1
	v_pk_fma_f32 v[230:231], v[234:235], v[204:205], v[230:231]
	v_cvt_pk_f32_fp8_e32 v[234:235], v39
	v_pk_fma_f32 v[230:231], v[236:237], v[206:207], v[230:231]
	v_cvt_pk_f32_fp8_sdwa v[236:237], v39 src0_sel:WORD_1
	v_pk_fma_f32 v[230:231], v[238:239], v[208:209], v[230:231]
	v_cvt_pk_f32_fp8_sdwa v[238:239], v41 src0_sel:WORD_1
	v_add_f32_e32 v183, v230, v231
	v_cvt_pk_f32_fp8_e32 v[230:231], v38
	v_pk_fma_f32 v[230:231], v[230:231], v[210:211], 0 op_sel_hi:[1,1,0]
	s_nop 0
	v_pk_fma_f32 v[230:231], v[232:233], v[212:213], v[230:231]
	v_cvt_pk_f32_fp8_e32 v[232:233], v40
; DI void dn2_math(const u32x4 (&W)[16], u32x4 x0, u32x4 x1, float* __restrict__ parow, int lane) {
;     ...
;   for (int j = 0; j < 16; ++j) {
;     f2 s2 = {0.f, 0.f};
; #pragma unroll
;     for (int d = 0; d < 4; ++d) {
;       f2 lo = __builtin_amdgcn_cvt_pk_f32_fp8((int)W[j][d], false);
;       f2 hi = __builtin_amdgcn_cvt_pk_f32_fp8((int)W[j][d], true);
;       s2 = lo * xf[2 * d] + s2;
;       s2 = hi * xf[2 * d + 1] + s2;
;     }
;     pv[j] = s2.x + s2.y;
;   }
	v_pk_fma_f32 v[230:231], v[234:235], v[214:215], v[230:231]
	v_cvt_pk_f32_fp8_sdwa v[234:235], v40 src0_sel:WORD_1
	v_pk_fma_f32 v[230:231], v[236:237], v[216:217], v[230:231]
	v_cvt_pk_f32_fp8_e32 v[236:237], v41
	v_pk_fma_f32 v[230:231], v[232:233], v[202:203], v[230:231]
	v_cvt_pk_f32_fp8_sdwa v[232:233], v42 src0_sel:WORD_1
	v_pk_fma_f32 v[230:231], v[234:235], v[204:205], v[230:231]
	v_cvt_pk_f32_fp8_e32 v[234:235], v43
	v_pk_fma_f32 v[230:231], v[236:237], v[206:207], v[230:231]
	v_cvt_pk_f32_fp8_sdwa v[236:237], v43 src0_sel:WORD_1
	v_pk_fma_f32 v[230:231], v[238:239], v[208:209], v[230:231]
	v_cvt_pk_f32_fp8_sdwa v[238:239], v45 src0_sel:WORD_1
	v_add_f32_e32 v185, v230, v231
	v_cvt_pk_f32_fp8_e32 v[230:231], v42
	v_pk_fma_f32 v[230:231], v[230:231], v[210:211], 0 op_sel_hi:[1,1,0]
	s_nop 0
	v_pk_fma_f32 v[230:231], v[232:233], v[212:213], v[230:231]
	v_cvt_pk_f32_fp8_e32 v[232:233], v44
	v_pk_fma_f32 v[230:231], v[234:235], v[214:215], v[230:231]
	v_cvt_pk_f32_fp8_sdwa v[234:235], v44 src0_sel:WORD_1
	v_pk_fma_f32 v[230:231], v[236:237], v[216:217], v[230:231]
	v_cvt_pk_f32_fp8_e32 v[236:237], v45
	v_pk_fma_f32 v[230:231], v[232:233], v[202:203], v[230:231]
	v_cvt_pk_f32_fp8_sdwa v[232:233], v46 src0_sel:WORD_1
	v_pk_fma_f32 v[230:231], v[234:235], v[204:205], v[230:231]
	v_cvt_pk_f32_fp8_e32 v[234:235], v47
	v_pk_fma_f32 v[230:231], v[236:237], v[206:207], v[230:231]
	v_cvt_pk_f32_fp8_sdwa v[236:237], v47 src0_sel:WORD_1
	v_pk_fma_f32 v[230:231], v[238:239], v[208:209], v[230:231]
	v_cvt_pk_f32_fp8_sdwa v[238:239], v49 src0_sel:WORD_1
	v_add_f32_e32 v187, v230, v231
	v_cvt_pk_f32_fp8_e32 v[230:231], v46
	v_pk_fma_f32 v[230:231], v[230:231], v[210:211], 0 op_sel_hi:[1,1,0]
	s_nop 0
	v_pk_fma_f32 v[230:231], v[232:233], v[212:213], v[230:231]
	v_cvt_pk_f32_fp8_e32 v[232:233], v48
	v_pk_fma_f32 v[230:231], v[234:235], v[214:215], v[230:231]
	v_cvt_pk_f32_fp8_sdwa v[234:235], v48 src0_sel:WORD_1
	v_pk_fma_f32 v[230:231], v[236:237], v[216:217], v[230:231]
	v_cvt_pk_f32_fp8_e32 v[236:237], v49
	v_pk_fma_f32 v[230:231], v[232:233], v[202:203], v[230:231]
	v_cvt_pk_f32_fp8_sdwa v[232:233], v50 src0_sel:WORD_1
	v_pk_fma_f32 v[230:231], v[234:235], v[204:205], v[230:231]
	v_cvt_pk_f32_fp8_e32 v[234:235], v51
	v_pk_fma_f32 v[230:231], v[236:237], v[206:207], v[230:231]
	v_cvt_pk_f32_fp8_sdwa v[236:237], v51 src0_sel:WORD_1
	v_pk_fma_f32 v[230:231], v[238:239], v[208:209], v[230:231]
	v_cvt_pk_f32_fp8_sdwa v[238:239], v53 src0_sel:WORD_1
	v_add_f32_e32 v189, v230, v231
	v_cvt_pk_f32_fp8_e32 v[230:231], v50
	v_pk_fma_f32 v[230:231], v[230:231], v[210:211], 0 op_sel_hi:[1,1,0]
	s_nop 0
	v_pk_fma_f32 v[230:231], v[232:233], v[212:213], v[230:231]
	v_cvt_pk_f32_fp8_e32 v[232:233], v52
	v_pk_fma_f32 v[230:231], v[234:235], v[214:215], v[230:231]
	v_cvt_pk_f32_fp8_sdwa v[234:235], v52 src0_sel:WORD_1
	v_pk_fma_f32 v[230:231], v[236:237], v[216:217], v[230:231]
	v_cvt_pk_f32_fp8_e32 v[236:237], v53
	v_pk_fma_f32 v[230:231], v[232:233], v[202:203], v[230:231]
	v_cvt_pk_f32_fp8_sdwa v[232:233], v54 src0_sel:WORD_1
	v_pk_fma_f32 v[230:231], v[234:235], v[204:205], v[230:231]
	v_cvt_pk_f32_fp8_e32 v[234:235], v55
	v_pk_fma_f32 v[230:231], v[236:237], v[206:207], v[230:231]
	v_cvt_pk_f32_fp8_sdwa v[236:237], v55 src0_sel:WORD_1
	v_pk_fma_f32 v[230:231], v[238:239], v[208:209], v[230:231]
	v_cvt_pk_f32_fp8_sdwa v[238:239], v57 src0_sel:WORD_1
	v_add_f32_e32 v229, v230, v231
	v_cvt_pk_f32_fp8_e32 v[230:231], v54
	v_pk_fma_f32 v[230:231], v[230:231], v[210:211], 0 op_sel_hi:[1,1,0]
	s_nop 0
	v_pk_fma_f32 v[230:231], v[232:233], v[212:213], v[230:231]
	v_cvt_pk_f32_fp8_e32 v[232:233], v56
	v_pk_fma_f32 v[230:231], v[234:235], v[214:215], v[230:231]
	v_cvt_pk_f32_fp8_sdwa v[234:235], v56 src0_sel:WORD_1
	v_pk_fma_f32 v[230:231], v[236:237], v[216:217], v[230:231]
	v_cvt_pk_f32_fp8_e32 v[236:237], v57
	v_pk_fma_f32 v[230:231], v[232:233], v[202:203], v[230:231]
	v_cvt_pk_f32_fp8_sdwa v[232:233], v58 src0_sel:WORD_1
	v_pk_fma_f32 v[230:231], v[234:235], v[204:205], v[230:231]
	v_cvt_pk_f32_fp8_e32 v[234:235], v59
	v_pk_fma_f32 v[230:231], v[236:237], v[206:207], v[230:231]
	v_cvt_pk_f32_fp8_sdwa v[236:237], v59 src0_sel:WORD_1
	v_pk_fma_f32 v[230:231], v[238:239], v[208:209], v[230:231]
	v_cvt_pk_f32_fp8_sdwa v[238:239], v61 src0_sel:WORD_1
	v_add_f32_e32 v240, v230, v231
	v_cvt_pk_f32_fp8_e32 v[230:231], v58
	v_pk_fma_f32 v[230:231], v[230:231], v[210:211], 0 op_sel_hi:[1,1,0]
	s_nop 0
	v_pk_fma_f32 v[230:231], v[232:233], v[212:213], v[230:231]
	v_cvt_pk_f32_fp8_e32 v[232:233], v60
	v_pk_fma_f32 v[230:231], v[234:235], v[214:215], v[230:231]
	v_cvt_pk_f32_fp8_sdwa v[234:235], v60 src0_sel:WORD_1
	v_pk_fma_f32 v[230:231], v[236:237], v[216:217], v[230:231]
	v_cvt_pk_f32_fp8_e32 v[236:237], v61
	v_pk_fma_f32 v[230:231], v[232:233], v[202:203], v[230:231]
	v_cvt_pk_f32_fp8_sdwa v[232:233], v62 src0_sel:WORD_1
	v_pk_fma_f32 v[230:231], v[234:235], v[204:205], v[230:231]
	v_cvt_pk_f32_fp8_e32 v[234:235], v63
	v_pk_fma_f32 v[230:231], v[236:237], v[206:207], v[230:231]
	v_cvt_pk_f32_fp8_sdwa v[236:237], v63 src0_sel:WORD_1
	v_pk_fma_f32 v[230:231], v[238:239], v[208:209], v[230:231]
	s_nop 0
	v_add_f32_e32 v238, v230, v231
	v_cvt_pk_f32_fp8_e32 v[230:231], v62
	v_pk_fma_f32 v[210:211], v[230:231], v[210:211], 0 op_sel_hi:[1,1,0]
; DI void dn2_issue(u32x4 (&W)[16], const int* pl, const unsigned char* wbase, int grp) {
; #pragma unroll
;   for (int j = 0; j < 16; ++j) W[j] = *(const u32x4*)(wbase + (size_t)pl[8 * j + grp] * 1024);
; }
; DI void dn2_math(const u32x4 (&W)[16], u32x4 x0, u32x4 x1, float* __restrict__ parow, int lane) {
;     ...
;   for (int j = 0; j < 16; ++j) {
;     f2 s2 = {0.f, 0.f};
; #pragma unroll
;     for (int d = 0; d < 4; ++d) {
;       f2 lo = __builtin_amdgcn_cvt_pk_f32_fp8((int)W[j][d], false);
;       f2 hi = __builtin_amdgcn_cvt_pk_f32_fp8((int)W[j][d], true);
;       s2 = lo * xf[2 * d] + s2;
;       s2 = hi * xf[2 * d + 1] + s2;
;     }
;     pv[j] = s2.x + s2.y;
;   }
;   const bool b2 = lane & 4, b1 = lane & 2, b0 = lane & 1;
;   float q8[8];
; #pragma unroll
;   for (int i = 0; i < 8; ++i) { float snd = b2 ? pv[i] : pv[i + 8]; float kp = b2 ? pv[i + 8] : pv[i]; q8[i] = kp + __shfl_xor(snd, 4); }
;   float q4[4];
; #pragma unroll
;   for (int i = 0; i < 4; ++i) { float snd = b1 ? q8[i] : q8[i + 4]; float kp = b1 ? q8[i + 4] : q8[i]; q4[i] = kp + __shfl_xor(snd, 2); }
;   float r2[2];
; #pragma unroll
;   for (int i = 0; i < 2; ++i) { float snd = b0 ? q4[i] : q4[i + 2]; float kp = b0 ? q4[i + 2] : q4[i]; r2[i] = kp + __shfl_xor(snd, 1); }
;   const int j0 = (b0 ? 2 : 0) + (b1 ? 4 : 0) + (b2 ? 8 : 0);
;   const int grp = lane >> 3;
;   parow[8 * j0 + grp] = r2[0];
;   parow[8 * (j0 + 1) + grp] = r2[1];
	s_nop 0
	v_pk_fma_f32 v[210:211], v[232:233], v[212:213], v[210:211]
	v_cvt_pk_f32_fp8_e32 v[212:213], v64
	v_pk_fma_f32 v[210:211], v[234:235], v[214:215], v[210:211]
	v_cvt_pk_f32_fp8_sdwa v[214:215], v64 src0_sel:WORD_1
	v_pk_fma_f32 v[210:211], v[236:237], v[216:217], v[210:211]
	v_cvt_pk_f32_fp8_e32 v[216:217], v65
	v_cvt_pk_f32_fp8_sdwa v[230:231], v65 src0_sel:WORD_1
	v_pk_fma_f32 v[202:203], v[212:213], v[202:203], v[210:211]
	s_nop 0
	v_pk_fma_f32 v[202:203], v[214:215], v[204:205], v[202:203]
	v_pk_fma_f32 v[202:203], v[216:217], v[206:207], v[202:203]
	v_pk_fma_f32 v[202:203], v[230:231], v[208:209], v[202:203]
	v_add_f32_e32 v202, v202, v203
	s_nop 1
	v_add_f32_dpp v167, v167, v167 row_shl:4 row_mask:0xf bank_mask:0x5
	v_add_f32_dpp v167, v183, v183 row_shr:4 row_mask:0xf bank_mask:0xa
	v_add_f32_dpp v173, v173, v173 row_shl:4 row_mask:0xf bank_mask:0x5
	v_add_f32_dpp v173, v189, v189 row_shr:4 row_mask:0xf bank_mask:0xa
	v_add_f32_dpp v175, v175, v175 row_shl:4 row_mask:0xf bank_mask:0x5
	v_add_f32_dpp v175, v229, v229 row_shr:4 row_mask:0xf bank_mask:0xa
	v_add_f32_dpp v169, v169, v169 row_shl:4 row_mask:0xf bank_mask:0x5
	v_add_f32_dpp v169, v185, v185 row_shr:4 row_mask:0xf bank_mask:0xa
	v_add_f32_dpp v171, v171, v171 row_shl:4 row_mask:0xf bank_mask:0x5
	v_add_f32_dpp v171, v187, v187 row_shr:4 row_mask:0xf bank_mask:0xa
	v_add_f32_dpp v177, v177, v177 row_shl:4 row_mask:0xf bank_mask:0x5
	v_add_f32_dpp v177, v240, v240 row_shr:4 row_mask:0xf bank_mask:0xa
	v_add_f32_dpp v179, v179, v179 row_shl:4 row_mask:0xf bank_mask:0x5
	v_add_f32_dpp v179, v238, v238 row_shr:4 row_mask:0xf bank_mask:0xa
	v_add_f32_dpp v181, v181, v181 row_shl:4 row_mask:0xf bank_mask:0x5
	v_add_f32_dpp v181, v202, v202 row_shr:4 row_mask:0xf bank_mask:0xa
	s_nop 1
	v_add_f32_dpp v167, v167, v167 quad_perm:[2,3,0,1] row_mask:0xf bank_mask:0xf
	v_add_f32_dpp v175, v175, v175 quad_perm:[2,3,0,1] row_mask:0xf bank_mask:0xf
	v_cndmask_b32_e64 v167, v175, v167, s[10:11]
	v_add_f32_dpp v171, v171, v171 quad_perm:[2,3,0,1] row_mask:0xf bank_mask:0xf
	v_add_f32_dpp v179, v179, v179 quad_perm:[2,3,0,1] row_mask:0xf bank_mask:0xf
	v_cndmask_b32_e64 v171, v179, v171, s[10:11]
	v_add_f32_dpp v169, v169, v169 quad_perm:[2,3,0,1] row_mask:0xf bank_mask:0xf
	v_add_f32_dpp v177, v177, v177 quad_perm:[2,3,0,1] row_mask:0xf bank_mask:0xf
	v_cndmask_b32_e64 v169, v177, v169, s[10:11]
	v_add_f32_dpp v173, v173, v173 quad_perm:[2,3,0,1] row_mask:0xf bank_mask:0xf
	v_add_f32_dpp v181, v181, v181 quad_perm:[2,3,0,1] row_mask:0xf bank_mask:0xf
	v_cndmask_b32_e64 v173, v181, v173, s[10:11]
	s_nop 1
	v_add_f32_dpp v167, v167, v167 quad_perm:[1,0,3,2] row_mask:0xf bank_mask:0xf
	v_add_f32_dpp v171, v171, v171 quad_perm:[1,0,3,2] row_mask:0xf bank_mask:0xf
	v_cndmask_b32_e64 v167, v171, v167, s[12:13]
	v_add_f32_dpp v169, v169, v169 quad_perm:[1,0,3,2] row_mask:0xf bank_mask:0xf
	v_add_f32_dpp v173, v173, v173 quad_perm:[1,0,3,2] row_mask:0xf bank_mask:0xf
	v_cndmask_b32_e64 v169, v173, v169, s[12:13]
	global_store_dword v[200:201], v167, off offset:-512
	global_store_dword v[200:201], v169, off offset:-480
	s_cmp_gt_u32 s40, 13
	s_cselect_b64 s[28:29], -1, 0
	s_and_b64 vcc, exec, s[28:29]
	s_cbranch_vccnz .LBB0_1516
	ds_read2_b32 v[2:3], v165 offset0:128 offset1:136
	ds_read2_b32 v[10:11], v165 offset0:144 offset1:152
	ds_read2_b32 v[18:19], v165 offset0:160 offset1:168
	ds_read2_b32 v[26:27], v165 offset0:176 offset1:184
	ds_read2_b32 v[34:35], v165 offset0:192 offset1:200
	ds_read2_b32 v[42:43], v165 offset0:208 offset1:216
	ds_read2_b32 v[50:51], v165 offset0:224 offset1:232
	ds_read2_b32 v[58:59], v165 offset0:240 offset1:248
	s_waitcnt lgkmcnt(7)
	v_lshl_add_u32 v6, v3, 10, v250
	v_lshl_add_u32 v2, v2, 10, v250
	global_load_dwordx4 v[2:5], v2, s[98:99]
	global_load_dwordx4 v[6:9], v6, s[98:99]
	s_waitcnt lgkmcnt(6)
	v_lshl_add_u32 v14, v11, 10, v250
	v_lshl_add_u32 v10, v10, 10, v250
	global_load_dwordx4 v[10:13], v10, s[98:99]
	global_load_dwordx4 v[14:17], v14, s[98:99]
	s_waitcnt lgkmcnt(5)
	v_lshl_add_u32 v22, v19, 10, v250
	v_lshl_add_u32 v18, v18, 10, v250
	global_load_dwordx4 v[18:21], v18, s[98:99]
	global_load_dwordx4 v[22:25], v22, s[98:99]
	s_waitcnt lgkmcnt(4)
	v_lshl_add_u32 v30, v27, 10, v250
	v_lshl_add_u32 v26, v26, 10, v250
	global_load_dwordx4 v[26:29], v26, s[98:99]
	global_load_dwordx4 v[30:33], v30, s[98:99]
	s_waitcnt lgkmcnt(3)
	v_lshl_add_u32 v38, v35, 10, v250
	v_lshl_add_u32 v34, v34, 10, v250
	global_load_dwordx4 v[34:37], v34, s[98:99]
	global_load_dwordx4 v[38:41], v38, s[98:99]
	s_waitcnt lgkmcnt(2)
	v_lshl_add_u32 v46, v43, 10, v250
	v_lshl_add_u32 v42, v42, 10, v250
	global_load_dwordx4 v[42:45], v42, s[98:99]
	global_load_dwordx4 v[46:49], v46, s[98:99]
	s_waitcnt lgkmcnt(1)
	v_lshl_add_u32 v54, v51, 10, v250
	v_lshl_add_u32 v50, v50, 10, v250
	global_load_dwordx4 v[50:53], v50, s[98:99]
	global_load_dwordx4 v[54:57], v54, s[98:99]
	s_waitcnt lgkmcnt(0)
	v_lshl_add_u32 v62, v59, 10, v250
	v_lshl_add_u32 v58, v58, 10, v250
	global_load_dwordx4 v[58:61], v58, s[98:99]
	global_load_dwordx4 v[62:65], v62, s[98:99]
	s_nop 0
	global_load_dwordx4 v[66:69], v[198:199], off offset:16
	global_load_dwordx4 v[70:73], v[198:199], off
	s_branch .LBB0_1516
